# v40 plus the mid-run s_setprio 0/1 pairs between the two 16-MFMA runs deleted
# baseline (speedup 1.0000x reference)
; #define PG8_STAGE(bufoff, gbase, voff) do { _Pragma("unroll") for (int _i = 0; _i < 2; ++_i) \
;         __builtin_amdgcn_global_load_lds((const unsigned*)((const char*)(gbase) + (voff)[_i]), (LAS unsigned*)(lds + (bufoff) + ldsw + _i * 8192), 16, 0, 0); } while (0)
; #define PG8_LDA(dst, b, h) do { _Pragma("unroll") for (int m = 0; m < NM; ++m) _Pragma("unroll") for (int k = 0; k < 2; ++k) dst[m][k] = *(const LAS bf16x8*)(lds + PG8_SA(b, h) + aoff + m * 2048 + k * 1024); } while (0)
; #define PG8_LDB(dst, b, h) do { _Pragma("unroll") for (int n = 0; n < 2; ++n) _Pragma("unroll") for (int k = 0; k < 2; ++k) dst[n][k] = *(const LAS bf16x8*)(lds + PG8_SB(b, h) + boff + n * 2048 + k * 1024); } while (0)
; #define PG8_MMA(ai, bj, At, Bt) do { __builtin_amdgcn_s_setprio(1); _Pragma("unroll") for (int m = 0; m < NM; ++m) _Pragma("unroll") for (int n = 0; n < 2; ++n) _Pragma("unroll") for (int k = 0; k < 2; ++k) \
;         acc[ai][bj][m][n] = __builtin_amdgcn_mfma_f32_16x16x32_bf16(Bt[n][k], At[m][k], acc[ai][bj][m][n], 0, 0, 0); __builtin_amdgcn_s_setprio(0); } while (0)
; #define PG8_WAIT_V(n) asm volatile("s_waitcnt vmcnt(" #n ")" ::: "memory")
; #define PG8_WAIT_L(n) asm volatile("s_waitcnt lgkmcnt(" #n ")" ::: "memory")
; #define PG8_BAR __builtin_amdgcn_s_barrier()
; #define PG8_SCHED __builtin_amdgcn_sched_barrier(0)
;     ...
;         for (int t = 0; t < nt; t += 2) {
;             const bool last = (t == nt - 2);
;             const char* a1 = cA + (size_t)(t + 1) * kstep;
;             const char* a2 = last ? nA : cA + (size_t)(t + 2) * kstep; const char* b2 = last ? nB : cB + (size_t)(t + 2) * kstep;
;             const char* a3 = a2 + kstep; const char* b3 = b2 + kstep;
;             if constexpr (SP2) {
;             PG8_LDB(B0, 0, 0); PG8_LDB(B1, 0, 1); PG8_SCHED; PG8_LDA(At, 0, 0); PG8_STAGE(PG8_SA(1, 1), a1 + hstepA, voffA);
;             PG8_WAIT_V(8); PG8_WAIT_L(0); PG8_BAR; PG8_MMA(0, 0, At, B0); PG8_MMA(0, 1, At, B1); PG8_BAR; PG8_SCHED;
;             PG8_LDA(At, 0, 1); PG8_STAGE(PG8_SB(0, 0), b2, voffB); PG8_STAGE(PG8_SB(0, 1), b2 + hstepB, voffB); PG8_STAGE(PG8_SA(0, 0), a2, voffA);
.LBB0_200:
	ds_read_b128 v[26:29], v172
	ds_read_b128 v[30:33], v172 offset:1024
	ds_read_b128 v[42:45], v172 offset:2048
	ds_read_b128 v[46:49], v172 offset:3072
	ds_read_b128 v[146:149], v173
	ds_read_b128 v[150:153], v173 offset:1024
	ds_read_b128 v[164:167], v173 offset:2048
	ds_read_b128 v[168:171], v173 offset:3072
	s_add_u32 s30, s28, 0xfff80080
	s_addc_u32 s31, s29, -1
	s_cmp_eq_u32 s56, 28
	s_cselect_b32 s35, s2, s31
	s_cselect_b32 s34, s3, s30
	s_cselect_b32 s31, s9, s54
	s_cselect_b32 s30, s21, s23
	s_cselect_b32 s100, -1, 0
	s_andn2_b32 s100, s100, s101
	s_add_i32 m0, s43, 0xc000
	ds_read_b128 v[178:181], v174
	ds_read_b128 v[182:185], v174 offset:1024
	ds_read_b128 v[186:189], v174 offset:2048
	ds_read_b128 v[190:193], v174 offset:3072
	ds_read_b128 v[194:197], v174 offset:4096
	ds_read_b128 v[198:201], v174 offset:5120
	ds_read_b128 v[202:205], v174 offset:6144
	ds_read_b128 v[206:209], v174 offset:7168
	global_load_lds_dwordx4 v160, s[28:29]
	s_add_i32 m0, s43, 0xe000
	s_nop 0
	global_load_lds_dwordx4 v162, s[28:29]
	s_waitcnt vmcnt(8)
	s_waitcnt lgkmcnt(0)
	s_setprio 1
	s_barrier
	v_mfma_f32_16x16x32_bf16 v[142:145], v[26:29], v[178:181], v[142:145]
	v_mfma_f32_16x16x32_bf16 v[138:141], v[42:45], v[178:181], v[138:141]
	v_mfma_f32_16x16x32_bf16 v[126:129], v[26:29], v[186:189], v[126:129]
	v_mfma_f32_16x16x32_bf16 v[122:125], v[42:45], v[186:189], v[122:125]
	v_mfma_f32_16x16x32_bf16 v[110:113], v[26:29], v[194:197], v[110:113]
	v_mfma_f32_16x16x32_bf16 v[106:109], v[42:45], v[194:197], v[106:109]
	v_mfma_f32_16x16x32_bf16 v[94:97], v[26:29], v[202:205], v[94:97]
	v_mfma_f32_16x16x32_bf16 v[90:93], v[42:45], v[202:205], v[90:93]
	v_mfma_f32_16x16x32_bf16 v[142:145], v[30:33], v[182:185], v[142:145]
	v_mfma_f32_16x16x32_bf16 v[138:141], v[46:49], v[182:185], v[138:141]
	v_mfma_f32_16x16x32_bf16 v[126:129], v[30:33], v[190:193], v[126:129]
	v_mfma_f32_16x16x32_bf16 v[122:125], v[46:49], v[190:193], v[122:125]
	v_mfma_f32_16x16x32_bf16 v[110:113], v[30:33], v[198:201], v[110:113]
	v_mfma_f32_16x16x32_bf16 v[106:109], v[46:49], v[198:201], v[106:109]
	v_mfma_f32_16x16x32_bf16 v[94:97], v[30:33], v[206:209], v[94:97]
	v_mfma_f32_16x16x32_bf16 v[90:93], v[46:49], v[206:209], v[90:93]
	v_mfma_f32_16x16x32_bf16 v[134:137], v[146:149], v[178:181], v[134:137]
	v_mfma_f32_16x16x32_bf16 v[130:133], v[164:167], v[178:181], v[130:133]
	v_mfma_f32_16x16x32_bf16 v[118:121], v[146:149], v[186:189], v[118:121]
	v_mfma_f32_16x16x32_bf16 v[114:117], v[164:167], v[186:189], v[114:117]
	v_mfma_f32_16x16x32_bf16 v[102:105], v[146:149], v[194:197], v[102:105]
	v_mfma_f32_16x16x32_bf16 v[98:101], v[164:167], v[194:197], v[98:101]
	v_mfma_f32_16x16x32_bf16 v[86:89], v[146:149], v[202:205], v[86:89]
	v_mfma_f32_16x16x32_bf16 v[82:85], v[164:167], v[202:205], v[82:85]
	v_mfma_f32_16x16x32_bf16 v[134:137], v[150:153], v[182:185], v[134:137]
	v_mfma_f32_16x16x32_bf16 v[130:133], v[168:171], v[182:185], v[130:133]
	v_mfma_f32_16x16x32_bf16 v[118:121], v[150:153], v[190:193], v[118:121]
	v_mfma_f32_16x16x32_bf16 v[114:117], v[168:171], v[190:193], v[114:117]
	v_mfma_f32_16x16x32_bf16 v[102:105], v[150:153], v[198:201], v[102:105]
	v_mfma_f32_16x16x32_bf16 v[98:101], v[168:171], v[198:201], v[98:101]
	v_mfma_f32_16x16x32_bf16 v[86:89], v[150:153], v[206:209], v[86:89]
	v_mfma_f32_16x16x32_bf16 v[82:85], v[168:171], v[206:209], v[82:85]
	s_barrier
	s_setprio 0
	s_mov_b32 m0, s39
	v_lshl_add_u64 v[210:211], s[30:31], 0, v[0:1]
	s_add_u32 s72, s30, 0x80000
	s_addc_u32 s73, s31, 0
	ds_read_b128 v[178:181], v174 offset:16384
	ds_read_b128 v[182:185], v174 offset:17408
	ds_read_b128 v[186:189], v174 offset:18432
	ds_read_b128 v[190:193], v174 offset:19456
	ds_read_b128 v[194:197], v174 offset:20480
	ds_read_b128 v[198:201], v174 offset:21504
	ds_read_b128 v[202:205], v174 offset:22528
	ds_read_b128 v[206:209], v174 offset:23552
	s_cmp_lg_u32 s100, 0
	s_cbranch_scc1 .Ltl_ic_0s
	global_load_lds_dwordx4 v0, s[30:31]
	v_lshl_add_u64 v[212:213], s[30:31], 0, v[158:159]
	s_mov_b32 m0, s40
	s_nop 0
	global_load_lds_dwordx4 v158, s[30:31]
	s_mov_b32 m0, s41
	v_lshl_add_u64 v[216:217], s[34:35], 0, v[156:157]
	global_load_lds_dwordx4 v0, s[72:73]
	s_mov_b32 m0, s42
	s_nop 0
	global_load_lds_dwordx4 v158, s[72:73]
	v_lshl_add_u64 v[214:215], s[34:35], 0, v[154:155]
	s_mov_b32 m0, s43
	s_nop 0
	global_load_lds_dwordx4 v154, s[34:35]
	s_mov_b32 m0, s44
	s_nop 0
	global_load_lds_dwordx4 v156, s[34:35]
	s_waitcnt vmcnt(8)
	s_branch .Ltl_ic_0d

; #define PG8_STAGE(bufoff, gbase, voff) do { _Pragma("unroll") for (int _i = 0; _i < 2; ++_i) \
;         __builtin_amdgcn_global_load_lds((const unsigned*)((const char*)(gbase) + (voff)[_i]), (LAS unsigned*)(lds + (bufoff) + ldsw + _i * 8192), 16, 0, 0); } while (0)
; #define PG8_LDA(dst, b, h) do { _Pragma("unroll") for (int m = 0; m < NM; ++m) _Pragma("unroll") for (int k = 0; k < 2; ++k) dst[m][k] = *(const LAS bf16x8*)(lds + PG8_SA(b, h) + aoff + m * 2048 + k * 1024); } while (0)
; #define PG8_LDB(dst, b, h) do { _Pragma("unroll") for (int n = 0; n < 2; ++n) _Pragma("unroll") for (int k = 0; k < 2; ++k) dst[n][k] = *(const LAS bf16x8*)(lds + PG8_SB(b, h) + boff + n * 2048 + k * 1024); } while (0)
; #define PG8_MMA(ai, bj, At, Bt) do { __builtin_amdgcn_s_setprio(1); _Pragma("unroll") for (int m = 0; m < NM; ++m) _Pragma("unroll") for (int n = 0; n < 2; ++n) _Pragma("unroll") for (int k = 0; k < 2; ++k) \
;         acc[ai][bj][m][n] = __builtin_amdgcn_mfma_f32_16x16x32_bf16(Bt[n][k], At[m][k], acc[ai][bj][m][n], 0, 0, 0); __builtin_amdgcn_s_setprio(0); } while (0)
; #define PG8_WAIT_V(n) asm volatile("s_waitcnt vmcnt(" #n ")" ::: "memory")
; #define PG8_WAIT_L(n) asm volatile("s_waitcnt lgkmcnt(" #n ")" ::: "memory")
; #define PG8_BAR __builtin_amdgcn_s_barrier()
; #define PG8_SCHED __builtin_amdgcn_sched_barrier(0)
;     ...
;             PG8_WAIT_V(8); PG8_WAIT_L(0); PG8_BAR; PG8_MMA(1, 0, At, B0); PG8_MMA(1, 1, At, B1); PG8_BAR; PG8_SCHED;
;             PG8_LDB(B0, 1, 0); PG8_LDB(B1, 1, 1); PG8_SCHED; PG8_LDA(At, 1, 0); PG8_STAGE(PG8_SA(0, 1), a2 + hstepA, voffA);
.Ltl_ic_0d:
	s_waitcnt lgkmcnt(0)
	s_setprio 1
	s_barrier
	v_mfma_f32_16x16x32_bf16 v[78:81], v[26:29], v[178:181], v[78:81]
	v_mfma_f32_16x16x32_bf16 v[74:77], v[42:45], v[178:181], v[74:77]
	v_mfma_f32_16x16x32_bf16 v[62:65], v[26:29], v[186:189], v[62:65]
	v_mfma_f32_16x16x32_bf16 v[58:61], v[42:45], v[186:189], v[58:61]
	v_mfma_f32_16x16x32_bf16 v[38:41], v[26:29], v[194:197], v[38:41]
	v_mfma_f32_16x16x32_bf16 v[34:37], v[42:45], v[194:197], v[34:37]
	v_mfma_f32_16x16x32_bf16 v[14:17], v[26:29], v[202:205], v[14:17]
	v_mfma_f32_16x16x32_bf16 v[10:13], v[42:45], v[202:205], v[10:13]
	v_mfma_f32_16x16x32_bf16 v[78:81], v[30:33], v[182:185], v[78:81]
	v_mfma_f32_16x16x32_bf16 v[74:77], v[46:49], v[182:185], v[74:77]
	v_mfma_f32_16x16x32_bf16 v[62:65], v[30:33], v[190:193], v[62:65]
	v_mfma_f32_16x16x32_bf16 v[58:61], v[46:49], v[190:193], v[58:61]
	v_mfma_f32_16x16x32_bf16 v[38:41], v[30:33], v[198:201], v[38:41]
	v_mfma_f32_16x16x32_bf16 v[34:37], v[46:49], v[198:201], v[34:37]
	v_mfma_f32_16x16x32_bf16 v[14:17], v[30:33], v[206:209], v[14:17]
	v_mfma_f32_16x16x32_bf16 v[10:13], v[46:49], v[206:209], v[10:13]
	v_mfma_f32_16x16x32_bf16 v[22:25], v[146:149], v[194:197], v[22:25]
	v_mfma_f32_16x16x32_bf16 v[18:21], v[164:167], v[194:197], v[18:21]
	v_mfma_f32_16x16x32_bf16 v[6:9], v[146:149], v[202:205], v[6:9]
	v_mfma_f32_16x16x32_bf16 v[2:5], v[164:167], v[202:205], v[2:5]
	v_mfma_f32_16x16x32_bf16 v[26:29], v[146:149], v[178:181], v[70:73]
	v_mfma_f32_16x16x32_bf16 v[30:33], v[164:167], v[178:181], v[66:69]
	v_mfma_f32_16x16x32_bf16 v[42:45], v[146:149], v[186:189], v[54:57]
	v_mfma_f32_16x16x32_bf16 v[46:49], v[164:167], v[186:189], v[50:53]
	v_mfma_f32_16x16x32_bf16 v[22:25], v[150:153], v[198:201], v[22:25]
	v_mfma_f32_16x16x32_bf16 v[18:21], v[168:171], v[198:201], v[18:21]
	v_mfma_f32_16x16x32_bf16 v[6:9], v[150:153], v[206:209], v[6:9]
	v_mfma_f32_16x16x32_bf16 v[2:5], v[168:171], v[206:209], v[2:5]
	v_mfma_f32_16x16x32_bf16 v[26:29], v[150:153], v[182:185], v[26:29]
	v_mfma_f32_16x16x32_bf16 v[30:33], v[168:171], v[182:185], v[30:33]
	v_mfma_f32_16x16x32_bf16 v[42:45], v[150:153], v[190:193], v[42:45]
	v_mfma_f32_16x16x32_bf16 v[46:49], v[168:171], v[190:193], v[46:49]
	s_barrier
	s_setprio 0
	ds_read_b128 v[50:53], v175
	ds_read_b128 v[54:57], v175 offset:1024
	ds_read_b128 v[66:69], v175 offset:2048
	ds_read_b128 v[70:73], v175 offset:3072
	ds_read_b128 v[146:149], v176
	ds_read_b128 v[150:153], v176 offset:1024
	ds_read_b128 v[164:167], v176 offset:2048
	ds_read_b128 v[168:171], v176 offset:3072
	s_add_u32 s34, s34, 0x80000
	s_addc_u32 s35, s35, 0
	s_mov_b32 m0, s45
	ds_read_b128 v[178:181], v174 offset:32768
	ds_read_b128 v[182:185], v174 offset:33792
	ds_read_b128 v[186:189], v174 offset:34816
	ds_read_b128 v[190:193], v174 offset:35840
	ds_read_b128 v[194:197], v174 offset:36864
	ds_read_b128 v[198:201], v174 offset:37888
	ds_read_b128 v[202:205], v174 offset:38912
	ds_read_b128 v[206:209], v174 offset:39936
	s_cmp_lg_u32 s100, 0
	s_cbranch_scc1 .Ltl_ic_1s
	global_load_lds_dwordx4 v154, s[34:35]
	s_mov_b32 m0, s46
	s_nop 0
	global_load_lds_dwordx4 v156, s[34:35]
	s_waitcnt vmcnt(8)
	s_branch .Ltl_ic_1d

; #define PG8_STAGE(bufoff, gbase, voff) do { _Pragma("unroll") for (int _i = 0; _i < 2; ++_i) \
;         __builtin_amdgcn_global_load_lds((const unsigned*)((const char*)(gbase) + (voff)[_i]), (LAS unsigned*)(lds + (bufoff) + ldsw + _i * 8192), 16, 0, 0); } while (0)
; #define PG8_LDA(dst, b, h) do { _Pragma("unroll") for (int m = 0; m < NM; ++m) _Pragma("unroll") for (int k = 0; k < 2; ++k) dst[m][k] = *(const LAS bf16x8*)(lds + PG8_SA(b, h) + aoff + m * 2048 + k * 1024); } while (0)
; #define PG8_MMA(ai, bj, At, Bt) do { __builtin_amdgcn_s_setprio(1); _Pragma("unroll") for (int m = 0; m < NM; ++m) _Pragma("unroll") for (int n = 0; n < 2; ++n) _Pragma("unroll") for (int k = 0; k < 2; ++k) \
;         acc[ai][bj][m][n] = __builtin_amdgcn_mfma_f32_16x16x32_bf16(Bt[n][k], At[m][k], acc[ai][bj][m][n], 0, 0, 0); __builtin_amdgcn_s_setprio(0); } while (0)
; #define PG8_WAIT_V(n) asm volatile("s_waitcnt vmcnt(" #n ")" ::: "memory")
; #define PG8_WAIT_L(n) asm volatile("s_waitcnt lgkmcnt(" #n ")" ::: "memory")
; #define PG8_BAR __builtin_amdgcn_s_barrier()
; #define PG8_SCHED __builtin_amdgcn_sched_barrier(0)
;     ...
;             PG8_WAIT_V(8); PG8_WAIT_L(0); PG8_BAR; PG8_MMA(0, 0, At, B0); PG8_MMA(0, 1, At, B1); PG8_BAR; PG8_SCHED;
;             PG8_LDA(At, 1, 1); PG8_STAGE(PG8_SB(1, 0), b3, voffB); PG8_STAGE(PG8_SB(1, 1), b3 + hstepB, voffB); PG8_STAGE(PG8_SA(1, 0), a3, voffA);
.Ltl_ic_1d:
	s_waitcnt lgkmcnt(0)
	s_setprio 1
	s_barrier
	v_mfma_f32_16x16x32_bf16 v[142:145], v[50:53], v[178:181], v[142:145]
	v_mfma_f32_16x16x32_bf16 v[138:141], v[66:69], v[178:181], v[138:141]
	v_mfma_f32_16x16x32_bf16 v[126:129], v[50:53], v[186:189], v[126:129]
	v_mfma_f32_16x16x32_bf16 v[122:125], v[66:69], v[186:189], v[122:125]
	v_mfma_f32_16x16x32_bf16 v[110:113], v[50:53], v[194:197], v[110:113]
	v_mfma_f32_16x16x32_bf16 v[106:109], v[66:69], v[194:197], v[106:109]
	v_mfma_f32_16x16x32_bf16 v[94:97], v[50:53], v[202:205], v[94:97]
	v_mfma_f32_16x16x32_bf16 v[90:93], v[66:69], v[202:205], v[90:93]
	v_mfma_f32_16x16x32_bf16 v[142:145], v[54:57], v[182:185], v[142:145]
	v_mfma_f32_16x16x32_bf16 v[138:141], v[70:73], v[182:185], v[138:141]
	v_mfma_f32_16x16x32_bf16 v[126:129], v[54:57], v[190:193], v[126:129]
	v_mfma_f32_16x16x32_bf16 v[122:125], v[70:73], v[190:193], v[122:125]
	v_mfma_f32_16x16x32_bf16 v[110:113], v[54:57], v[198:201], v[110:113]
	v_mfma_f32_16x16x32_bf16 v[106:109], v[70:73], v[198:201], v[106:109]
	v_mfma_f32_16x16x32_bf16 v[94:97], v[54:57], v[206:209], v[94:97]
	v_mfma_f32_16x16x32_bf16 v[90:93], v[70:73], v[206:209], v[90:93]
	v_mfma_f32_16x16x32_bf16 v[134:137], v[146:149], v[178:181], v[134:137]
	v_mfma_f32_16x16x32_bf16 v[130:133], v[164:167], v[178:181], v[130:133]
	v_mfma_f32_16x16x32_bf16 v[118:121], v[146:149], v[186:189], v[118:121]
	v_mfma_f32_16x16x32_bf16 v[114:117], v[164:167], v[186:189], v[114:117]
	v_mfma_f32_16x16x32_bf16 v[102:105], v[146:149], v[194:197], v[102:105]
	v_mfma_f32_16x16x32_bf16 v[98:101], v[164:167], v[194:197], v[98:101]
	v_mfma_f32_16x16x32_bf16 v[86:89], v[146:149], v[202:205], v[86:89]
	v_mfma_f32_16x16x32_bf16 v[82:85], v[164:167], v[202:205], v[82:85]
	v_mfma_f32_16x16x32_bf16 v[134:137], v[150:153], v[182:185], v[134:137]
	v_mfma_f32_16x16x32_bf16 v[130:133], v[168:171], v[182:185], v[130:133]
	v_mfma_f32_16x16x32_bf16 v[118:121], v[150:153], v[190:193], v[118:121]
	v_mfma_f32_16x16x32_bf16 v[114:117], v[168:171], v[190:193], v[114:117]
	v_mfma_f32_16x16x32_bf16 v[102:105], v[150:153], v[198:201], v[102:105]
	v_mfma_f32_16x16x32_bf16 v[98:101], v[168:171], v[198:201], v[98:101]
	v_mfma_f32_16x16x32_bf16 v[86:89], v[150:153], v[206:209], v[86:89]
	v_mfma_f32_16x16x32_bf16 v[82:85], v[168:171], v[206:209], v[82:85]
	s_barrier
	s_setprio 0
	s_mov_b32 m0, s49
	v_lshl_add_u64 v[210:211], v[210:211], 0, s[66:67]
	s_add_u32 s30, s30, 0x80080
	s_addc_u32 s31, s31, 0
	ds_read_b128 v[178:181], v174 offset:49152
	ds_read_b128 v[182:185], v174 offset:50176
	ds_read_b128 v[186:189], v174 offset:51200
	ds_read_b128 v[190:193], v174 offset:52224
	ds_read_b128 v[194:197], v174 offset:53248
	ds_read_b128 v[198:201], v174 offset:54272
	ds_read_b128 v[202:205], v174 offset:55296
	ds_read_b128 v[206:209], v174 offset:56320
	s_cmp_lg_u32 s100, 0
	s_cbranch_scc1 .Ltl_ic_2s
	global_load_lds_dwordx4 v[210:211], off
	v_lshl_add_u64 v[210:211], v[212:213], 0, s[66:67]
	s_mov_b32 m0, s50
	s_nop 0
	global_load_lds_dwordx4 v[210:211], off
	s_mov_b32 m0, s58
	s_nop 0
	global_load_lds_dwordx4 v0, s[30:31]
	s_mov_b32 m0, s59
	s_nop 0
	global_load_lds_dwordx4 v158, s[30:31]
	v_lshl_add_u64 v[210:211], v[214:215], 0, s[66:67]
	s_mov_b32 m0, s51
	s_nop 0
	global_load_lds_dwordx4 v[210:211], off
	v_lshl_add_u64 v[210:211], v[216:217], 0, s[66:67]
	s_mov_b32 m0, s52
	s_nop 0
	global_load_lds_dwordx4 v[210:211], off
	s_waitcnt vmcnt(8)
	s_branch .Ltl_ic_2d

; #define PG8_MMA(ai, bj, At, Bt) do { __builtin_amdgcn_s_setprio(1); _Pragma("unroll") for (int m = 0; m < NM; ++m) _Pragma("unroll") for (int n = 0; n < 2; ++n) _Pragma("unroll") for (int k = 0; k < 2; ++k) \
;         acc[ai][bj][m][n] = __builtin_amdgcn_mfma_f32_16x16x32_bf16(Bt[n][k], At[m][k], acc[ai][bj][m][n], 0, 0, 0); __builtin_amdgcn_s_setprio(0); } while (0)
; #define PG8_WAIT_V(n) asm volatile("s_waitcnt vmcnt(" #n ")" ::: "memory")
; #define PG8_WAIT_L(n) asm volatile("s_waitcnt lgkmcnt(" #n ")" ::: "memory")
; #define PG8_BAR __builtin_amdgcn_s_barrier()
; #define PG8_SCHED __builtin_amdgcn_sched_barrier(0)
;     ...
;             PG8_WAIT_V(8); PG8_WAIT_L(0); PG8_BAR; PG8_MMA(1, 0, At, B0); PG8_MMA(1, 1, At, B1); PG8_BAR; PG8_SCHED;
;     ...
;         }
;         if constexpr (ALIGN_EPI) { if (wr == 0) PG8_BAR; }
.Ltl_ic_2d:
	s_waitcnt lgkmcnt(0)
	s_setprio 1
	s_barrier
	v_mfma_f32_16x16x32_bf16 v[78:81], v[50:53], v[178:181], v[78:81]
	v_mfma_f32_16x16x32_bf16 v[74:77], v[66:69], v[178:181], v[74:77]
	v_mfma_f32_16x16x32_bf16 v[62:65], v[50:53], v[186:189], v[62:65]
	v_mfma_f32_16x16x32_bf16 v[58:61], v[66:69], v[186:189], v[58:61]
	v_mfma_f32_16x16x32_bf16 v[38:41], v[50:53], v[194:197], v[38:41]
	v_mfma_f32_16x16x32_bf16 v[34:37], v[66:69], v[194:197], v[34:37]
	v_mfma_f32_16x16x32_bf16 v[14:17], v[50:53], v[202:205], v[14:17]
	v_mfma_f32_16x16x32_bf16 v[10:13], v[66:69], v[202:205], v[10:13]
	v_mfma_f32_16x16x32_bf16 v[78:81], v[54:57], v[182:185], v[78:81]
	v_mfma_f32_16x16x32_bf16 v[74:77], v[70:73], v[182:185], v[74:77]
	v_mfma_f32_16x16x32_bf16 v[62:65], v[54:57], v[190:193], v[62:65]
	v_mfma_f32_16x16x32_bf16 v[58:61], v[70:73], v[190:193], v[58:61]
	v_mfma_f32_16x16x32_bf16 v[38:41], v[54:57], v[198:201], v[38:41]
	v_mfma_f32_16x16x32_bf16 v[34:37], v[70:73], v[198:201], v[34:37]
	v_mfma_f32_16x16x32_bf16 v[14:17], v[54:57], v[206:209], v[14:17]
	v_mfma_f32_16x16x32_bf16 v[10:13], v[70:73], v[206:209], v[10:13]
	v_mfma_f32_16x16x32_bf16 v[26:29], v[146:149], v[178:181], v[26:29]
	v_mfma_f32_16x16x32_bf16 v[70:73], v[150:153], v[182:185], v[26:29]
	v_mfma_f32_16x16x32_bf16 v[26:29], v[164:167], v[178:181], v[30:33]
	v_mfma_f32_16x16x32_bf16 v[66:69], v[168:171], v[182:185], v[26:29]
	v_mfma_f32_16x16x32_bf16 v[26:29], v[146:149], v[186:189], v[42:45]
	v_mfma_f32_16x16x32_bf16 v[54:57], v[150:153], v[190:193], v[26:29]
	v_mfma_f32_16x16x32_bf16 v[26:29], v[164:167], v[186:189], v[46:49]
	v_mfma_f32_16x16x32_bf16 v[22:25], v[146:149], v[194:197], v[22:25]
	v_mfma_f32_16x16x32_bf16 v[18:21], v[164:167], v[194:197], v[18:21]
	v_mfma_f32_16x16x32_bf16 v[6:9], v[146:149], v[202:205], v[6:9]
	v_mfma_f32_16x16x32_bf16 v[2:5], v[164:167], v[202:205], v[2:5]
	v_mfma_f32_16x16x32_bf16 v[50:53], v[168:171], v[190:193], v[26:29]
	v_mfma_f32_16x16x32_bf16 v[22:25], v[150:153], v[198:201], v[22:25]
	v_mfma_f32_16x16x32_bf16 v[18:21], v[168:171], v[198:201], v[18:21]
	v_mfma_f32_16x16x32_bf16 v[6:9], v[150:153], v[206:209], v[6:9]
	v_mfma_f32_16x16x32_bf16 v[2:5], v[168:171], v[206:209], v[2:5]
	s_barrier
	s_setprio 0
	s_add_i32 s56, s56, 2
	s_add_u32 s28, s28, 0x100
	s_addc_u32 s29, s29, 0
	s_add_u32 s23, s23, 0x100
	s_addc_u32 s54, s54, 0
	s_cmp_gt_u32 s56, 29
	s_cbranch_scc0 .LBB0_200
	s_and_b64 vcc, exec, s[14:15]
	s_cbranch_vccz .LBB0_203
	s_barrier

; #define PG8_STAGE(bufoff, gbase, voff) do { _Pragma("unroll") for (int _i = 0; _i < 2; ++_i) \
;         __builtin_amdgcn_global_load_lds((const unsigned*)((const char*)(gbase) + (voff)[_i]), (LAS unsigned*)(lds + (bufoff) + ldsw + _i * 8192), 16, 0, 0); } while (0)
; #define PG8_LDA(dst, b, h) do { _Pragma("unroll") for (int m = 0; m < NM; ++m) _Pragma("unroll") for (int k = 0; k < 2; ++k) dst[m][k] = *(const LAS bf16x8*)(lds + PG8_SA(b, h) + aoff + m * 2048 + k * 1024); } while (0)
; #define PG8_LDB(dst, b, h) do { _Pragma("unroll") for (int n = 0; n < 2; ++n) _Pragma("unroll") for (int k = 0; k < 2; ++k) dst[n][k] = *(const LAS bf16x8*)(lds + PG8_SB(b, h) + boff + n * 2048 + k * 1024); } while (0)
; #define PG8_MMA(ai, bj, At, Bt) do { __builtin_amdgcn_s_setprio(1); _Pragma("unroll") for (int m = 0; m < NM; ++m) _Pragma("unroll") for (int n = 0; n < 2; ++n) _Pragma("unroll") for (int k = 0; k < 2; ++k) \
;         acc[ai][bj][m][n] = __builtin_amdgcn_mfma_f32_16x16x32_bf16(Bt[n][k], At[m][k], acc[ai][bj][m][n], 0, 0, 0); __builtin_amdgcn_s_setprio(0); } while (0)
; #define PG8_WAIT_V(n) asm volatile("s_waitcnt vmcnt(" #n ")" ::: "memory")
; #define PG8_WAIT_L(n) asm volatile("s_waitcnt lgkmcnt(" #n ")" ::: "memory")
; #define PG8_BAR __builtin_amdgcn_s_barrier()
; #define PG8_SCHED __builtin_amdgcn_sched_barrier(0)
;     ...
;         for (int t = 0; t < nt; t += 2) {
;             const bool last = (t == nt - 2);
;             const char* a1 = cA + (size_t)(t + 1) * kstep;
;             const char* a2 = last ? nA : cA + (size_t)(t + 2) * kstep; const char* b2 = last ? nB : cB + (size_t)(t + 2) * kstep;
;             const char* a3 = a2 + kstep; const char* b3 = b2 + kstep;
;             if constexpr (SP2) {
;             PG8_LDB(B0, 0, 0); PG8_LDB(B1, 0, 1); PG8_SCHED; PG8_LDA(At, 0, 0); PG8_STAGE(PG8_SA(1, 1), a1 + hstepA, voffA);
;             PG8_WAIT_V(8); PG8_WAIT_L(0); PG8_BAR; PG8_MMA(0, 0, At, B0); PG8_MMA(0, 1, At, B1); PG8_BAR; PG8_SCHED;
;             PG8_LDA(At, 0, 1); PG8_STAGE(PG8_SB(0, 0), b2, voffB); PG8_STAGE(PG8_SB(0, 1), b2 + hstepB, voffB); PG8_STAGE(PG8_SA(0, 0), a2, voffA);
.LBB0_703:
	v_add_u32_e32 v0, s50, v146
	ds_read_b128 v[138:141], v0
	ds_read_b128 v[142:145], v0 offset:1024
	ds_read_b128 v[148:151], v0 offset:2048
	ds_read_b128 v[152:155], v0 offset:3072
	v_add_u32_e32 v0, s54, v146
	ds_read_b128 v[156:159], v0
	ds_read_b128 v[160:163], v0 offset:1024
	ds_read_b128 v[164:167], v0 offset:2048
	ds_read_b128 v[168:171], v0 offset:3072
	s_add_u32 s12, s10, 0xfff80080
	s_addc_u32 s13, s11, -1
	s_cmp_eq_u32 s39, 28
	s_cselect_b32 s37, s2, s13
	s_cselect_b32 s36, s3, s12
	s_cselect_b32 s13, s9, s38
	s_cselect_b32 s12, s27, s29
	s_cselect_b32 s100, -1, 0
	s_andn2_b32 s100, s100, s101
	s_add_i32 m0, s58, 0xc000
	ds_read_b128 v[172:175], v147
	ds_read_b128 v[176:179], v147 offset:1024
	ds_read_b128 v[180:183], v147 offset:2048
	ds_read_b128 v[184:187], v147 offset:3072
	ds_read_b128 v[188:191], v147 offset:4096
	ds_read_b128 v[192:195], v147 offset:5120
	ds_read_b128 v[196:199], v147 offset:6144
	ds_read_b128 v[200:203], v147 offset:7168
	global_load_lds_dwordx4 v134, s[10:11]
	s_add_i32 m0, s58, 0xe000
	s_nop 0
	global_load_lds_dwordx4 v136, s[10:11]
	s_waitcnt vmcnt(8)
	s_waitcnt lgkmcnt(0)
	s_setprio 1
	s_barrier
	v_mfma_f32_16x16x32_bf16 v[126:129], v[138:141], v[172:175], v[126:129]
	v_mfma_f32_16x16x32_bf16 v[122:125], v[148:151], v[172:175], v[122:125]
	v_mfma_f32_16x16x32_bf16 v[110:113], v[138:141], v[180:183], v[110:113]
	v_mfma_f32_16x16x32_bf16 v[106:109], v[148:151], v[180:183], v[106:109]
	v_mfma_f32_16x16x32_bf16 v[94:97], v[138:141], v[188:191], v[94:97]
	v_mfma_f32_16x16x32_bf16 v[90:93], v[148:151], v[188:191], v[90:93]
	v_mfma_f32_16x16x32_bf16 v[78:81], v[138:141], v[196:199], v[78:81]
	v_mfma_f32_16x16x32_bf16 v[74:77], v[148:151], v[196:199], v[74:77]
	v_mfma_f32_16x16x32_bf16 v[126:129], v[142:145], v[176:179], v[126:129]
	v_mfma_f32_16x16x32_bf16 v[122:125], v[152:155], v[176:179], v[122:125]
	v_mfma_f32_16x16x32_bf16 v[110:113], v[142:145], v[184:187], v[110:113]
	v_mfma_f32_16x16x32_bf16 v[106:109], v[152:155], v[184:187], v[106:109]
	v_mfma_f32_16x16x32_bf16 v[94:97], v[142:145], v[192:195], v[94:97]
	v_mfma_f32_16x16x32_bf16 v[90:93], v[152:155], v[192:195], v[90:93]
	v_mfma_f32_16x16x32_bf16 v[78:81], v[142:145], v[200:203], v[78:81]
	v_mfma_f32_16x16x32_bf16 v[74:77], v[152:155], v[200:203], v[74:77]
	v_mfma_f32_16x16x32_bf16 v[118:121], v[156:159], v[172:175], v[118:121]
	v_mfma_f32_16x16x32_bf16 v[114:117], v[164:167], v[172:175], v[114:117]
	v_mfma_f32_16x16x32_bf16 v[102:105], v[156:159], v[180:183], v[102:105]
	v_mfma_f32_16x16x32_bf16 v[98:101], v[164:167], v[180:183], v[98:101]
	v_mfma_f32_16x16x32_bf16 v[86:89], v[156:159], v[188:191], v[86:89]
	v_mfma_f32_16x16x32_bf16 v[82:85], v[164:167], v[188:191], v[82:85]
	v_mfma_f32_16x16x32_bf16 v[70:73], v[156:159], v[196:199], v[70:73]
	v_mfma_f32_16x16x32_bf16 v[66:69], v[164:167], v[196:199], v[66:69]
	v_mfma_f32_16x16x32_bf16 v[118:121], v[160:163], v[176:179], v[118:121]
	v_mfma_f32_16x16x32_bf16 v[114:117], v[168:171], v[176:179], v[114:117]
	v_mfma_f32_16x16x32_bf16 v[102:105], v[160:163], v[184:187], v[102:105]
	v_mfma_f32_16x16x32_bf16 v[98:101], v[168:171], v[184:187], v[98:101]
	v_mfma_f32_16x16x32_bf16 v[86:89], v[160:163], v[192:195], v[86:89]
	v_mfma_f32_16x16x32_bf16 v[82:85], v[168:171], v[192:195], v[82:85]
	v_mfma_f32_16x16x32_bf16 v[70:73], v[160:163], v[200:203], v[70:73]
	v_mfma_f32_16x16x32_bf16 v[66:69], v[168:171], v[200:203], v[66:69]
	s_barrier
	s_setprio 0
	s_mov_b32 m0, s51
	v_lshl_add_u64 v[204:205], s[12:13], 0, v[130:131]
	s_add_u32 s40, s12, 0x80000
	s_addc_u32 s41, s13, 0
	ds_read_b128 v[172:175], v147 offset:16384
	ds_read_b128 v[176:179], v147 offset:17408
	ds_read_b128 v[180:183], v147 offset:18432
	ds_read_b128 v[184:187], v147 offset:19456
	ds_read_b128 v[188:191], v147 offset:20480
	ds_read_b128 v[192:195], v147 offset:21504
	ds_read_b128 v[196:199], v147 offset:22528
	ds_read_b128 v[200:203], v147 offset:23552
	s_cmp_lg_u32 s100, 0
	s_cbranch_scc1 .Ltl_ia_0s
	global_load_lds_dwordx4 v130, s[12:13]
	v_lshl_add_u64 v[206:207], s[12:13], 0, v[132:133]
	s_mov_b32 m0, s52
	s_nop 0
	global_load_lds_dwordx4 v132, s[12:13]
	s_mov_b32 m0, s56
	v_lshl_add_u64 v[210:211], s[36:37], 0, v[132:133]
	global_load_lds_dwordx4 v130, s[40:41]
	s_mov_b32 m0, s57
	s_nop 0
	global_load_lds_dwordx4 v132, s[40:41]
	v_lshl_add_u64 v[208:209], s[36:37], 0, v[130:131]
	s_mov_b32 m0, s58
	s_nop 0
	global_load_lds_dwordx4 v130, s[36:37]
	s_mov_b32 m0, s59
	s_nop 0
	global_load_lds_dwordx4 v132, s[36:37]
	s_waitcnt vmcnt(8)
	s_branch .Ltl_ia_0d

; #define PG8_STAGE(bufoff, gbase, voff) do { _Pragma("unroll") for (int _i = 0; _i < 2; ++_i) \
;         __builtin_amdgcn_global_load_lds((const unsigned*)((const char*)(gbase) + (voff)[_i]), (LAS unsigned*)(lds + (bufoff) + ldsw + _i * 8192), 16, 0, 0); } while (0)
; #define PG8_LDA(dst, b, h) do { _Pragma("unroll") for (int m = 0; m < NM; ++m) _Pragma("unroll") for (int k = 0; k < 2; ++k) dst[m][k] = *(const LAS bf16x8*)(lds + PG8_SA(b, h) + aoff + m * 2048 + k * 1024); } while (0)
; #define PG8_LDB(dst, b, h) do { _Pragma("unroll") for (int n = 0; n < 2; ++n) _Pragma("unroll") for (int k = 0; k < 2; ++k) dst[n][k] = *(const LAS bf16x8*)(lds + PG8_SB(b, h) + boff + n * 2048 + k * 1024); } while (0)
; #define PG8_MMA(ai, bj, At, Bt) do { __builtin_amdgcn_s_setprio(1); _Pragma("unroll") for (int m = 0; m < NM; ++m) _Pragma("unroll") for (int n = 0; n < 2; ++n) _Pragma("unroll") for (int k = 0; k < 2; ++k) \
;         acc[ai][bj][m][n] = __builtin_amdgcn_mfma_f32_16x16x32_bf16(Bt[n][k], At[m][k], acc[ai][bj][m][n], 0, 0, 0); __builtin_amdgcn_s_setprio(0); } while (0)
; #define PG8_WAIT_V(n) asm volatile("s_waitcnt vmcnt(" #n ")" ::: "memory")
; #define PG8_WAIT_L(n) asm volatile("s_waitcnt lgkmcnt(" #n ")" ::: "memory")
; #define PG8_BAR __builtin_amdgcn_s_barrier()
; #define PG8_SCHED __builtin_amdgcn_sched_barrier(0)
;     ...
;             PG8_WAIT_V(8); PG8_WAIT_L(0); PG8_BAR; PG8_MMA(1, 0, At, B0); PG8_MMA(1, 1, At, B1); PG8_BAR; PG8_SCHED;
;             PG8_LDB(B0, 1, 0); PG8_LDB(B1, 1, 1); PG8_SCHED; PG8_LDA(At, 1, 0); PG8_STAGE(PG8_SA(0, 1), a2 + hstepA, voffA);
.Ltl_ia_0d:
	s_waitcnt lgkmcnt(0)
	s_setprio 1
	s_barrier
	v_mfma_f32_16x16x32_bf16 v[62:65], v[138:141], v[172:175], v[62:65]
	v_mfma_f32_16x16x32_bf16 v[58:61], v[148:151], v[172:175], v[58:61]
	v_mfma_f32_16x16x32_bf16 v[46:49], v[138:141], v[180:183], v[46:49]
	v_mfma_f32_16x16x32_bf16 v[42:45], v[148:151], v[180:183], v[42:45]
	v_mfma_f32_16x16x32_bf16 v[30:33], v[138:141], v[188:191], v[30:33]
	v_mfma_f32_16x16x32_bf16 v[26:29], v[148:151], v[188:191], v[26:29]
	v_mfma_f32_16x16x32_bf16 v[14:17], v[138:141], v[196:199], v[14:17]
	v_mfma_f32_16x16x32_bf16 v[10:13], v[148:151], v[196:199], v[10:13]
	v_mfma_f32_16x16x32_bf16 v[62:65], v[142:145], v[176:179], v[62:65]
	v_mfma_f32_16x16x32_bf16 v[58:61], v[152:155], v[176:179], v[58:61]
	v_mfma_f32_16x16x32_bf16 v[46:49], v[142:145], v[184:187], v[46:49]
	v_mfma_f32_16x16x32_bf16 v[42:45], v[152:155], v[184:187], v[42:45]
	v_mfma_f32_16x16x32_bf16 v[30:33], v[142:145], v[192:195], v[30:33]
	v_mfma_f32_16x16x32_bf16 v[26:29], v[152:155], v[192:195], v[26:29]
	v_mfma_f32_16x16x32_bf16 v[14:17], v[142:145], v[200:203], v[14:17]
	v_mfma_f32_16x16x32_bf16 v[10:13], v[152:155], v[200:203], v[10:13]
	v_mfma_f32_16x16x32_bf16 v[54:57], v[156:159], v[172:175], v[54:57]
	v_mfma_f32_16x16x32_bf16 v[50:53], v[164:167], v[172:175], v[50:53]
	v_mfma_f32_16x16x32_bf16 v[38:41], v[156:159], v[180:183], v[38:41]
	v_mfma_f32_16x16x32_bf16 v[34:37], v[164:167], v[180:183], v[34:37]
	v_mfma_f32_16x16x32_bf16 v[22:25], v[156:159], v[188:191], v[22:25]
	v_mfma_f32_16x16x32_bf16 v[18:21], v[164:167], v[188:191], v[18:21]
	v_mfma_f32_16x16x32_bf16 v[6:9], v[156:159], v[196:199], v[6:9]
	v_mfma_f32_16x16x32_bf16 v[2:5], v[164:167], v[196:199], v[2:5]
	v_mfma_f32_16x16x32_bf16 v[54:57], v[160:163], v[176:179], v[54:57]
	v_mfma_f32_16x16x32_bf16 v[50:53], v[168:171], v[176:179], v[50:53]
	v_mfma_f32_16x16x32_bf16 v[38:41], v[160:163], v[184:187], v[38:41]
	v_mfma_f32_16x16x32_bf16 v[34:37], v[168:171], v[184:187], v[34:37]
	v_mfma_f32_16x16x32_bf16 v[22:25], v[160:163], v[192:195], v[22:25]
	v_mfma_f32_16x16x32_bf16 v[18:21], v[168:171], v[192:195], v[18:21]
	v_mfma_f32_16x16x32_bf16 v[6:9], v[160:163], v[200:203], v[6:9]
	v_mfma_f32_16x16x32_bf16 v[2:5], v[168:171], v[200:203], v[2:5]
	s_barrier
	s_setprio 0
	v_add_u32_e32 v0, s64, v146
	ds_read_b128 v[138:141], v0
	ds_read_b128 v[142:145], v0 offset:1024
	ds_read_b128 v[148:151], v0 offset:2048
	ds_read_b128 v[152:155], v0 offset:3072
	v_add_u32_e32 v0, s71, v146
	ds_read_b128 v[156:159], v0
	ds_read_b128 v[160:163], v0 offset:1024
	ds_read_b128 v[164:167], v0 offset:2048
	ds_read_b128 v[168:171], v0 offset:3072
	s_add_u32 s36, s36, 0x80000
	s_addc_u32 s37, s37, 0
	s_mov_b32 m0, s62
	ds_read_b128 v[172:175], v147 offset:32768
	ds_read_b128 v[176:179], v147 offset:33792
	ds_read_b128 v[180:183], v147 offset:34816
	ds_read_b128 v[184:187], v147 offset:35840
	ds_read_b128 v[188:191], v147 offset:36864
	ds_read_b128 v[192:195], v147 offset:37888
	ds_read_b128 v[196:199], v147 offset:38912
	ds_read_b128 v[200:203], v147 offset:39936
	s_cmp_lg_u32 s100, 0
	s_cbranch_scc1 .Ltl_ia_1s
	global_load_lds_dwordx4 v130, s[36:37]
	s_mov_b32 m0, s63
	s_nop 0
	global_load_lds_dwordx4 v132, s[36:37]
	s_waitcnt vmcnt(8)
	s_branch .Ltl_ia_1d

; #define PG8_STAGE(bufoff, gbase, voff) do { _Pragma("unroll") for (int _i = 0; _i < 2; ++_i) \
;         __builtin_amdgcn_global_load_lds((const unsigned*)((const char*)(gbase) + (voff)[_i]), (LAS unsigned*)(lds + (bufoff) + ldsw + _i * 8192), 16, 0, 0); } while (0)
; #define PG8_LDA(dst, b, h) do { _Pragma("unroll") for (int m = 0; m < NM; ++m) _Pragma("unroll") for (int k = 0; k < 2; ++k) dst[m][k] = *(const LAS bf16x8*)(lds + PG8_SA(b, h) + aoff + m * 2048 + k * 1024); } while (0)
; #define PG8_MMA(ai, bj, At, Bt) do { __builtin_amdgcn_s_setprio(1); _Pragma("unroll") for (int m = 0; m < NM; ++m) _Pragma("unroll") for (int n = 0; n < 2; ++n) _Pragma("unroll") for (int k = 0; k < 2; ++k) \
;         acc[ai][bj][m][n] = __builtin_amdgcn_mfma_f32_16x16x32_bf16(Bt[n][k], At[m][k], acc[ai][bj][m][n], 0, 0, 0); __builtin_amdgcn_s_setprio(0); } while (0)
; #define PG8_WAIT_V(n) asm volatile("s_waitcnt vmcnt(" #n ")" ::: "memory")
; #define PG8_WAIT_L(n) asm volatile("s_waitcnt lgkmcnt(" #n ")" ::: "memory")
; #define PG8_BAR __builtin_amdgcn_s_barrier()
; #define PG8_SCHED __builtin_amdgcn_sched_barrier(0)
;     ...
;             PG8_WAIT_V(8); PG8_WAIT_L(0); PG8_BAR; PG8_MMA(0, 0, At, B0); PG8_MMA(0, 1, At, B1); PG8_BAR; PG8_SCHED;
;             PG8_LDA(At, 1, 1); PG8_STAGE(PG8_SB(1, 0), b3, voffB); PG8_STAGE(PG8_SB(1, 1), b3 + hstepB, voffB); PG8_STAGE(PG8_SA(1, 0), a3, voffA);
.Ltl_ia_1d:
	s_waitcnt lgkmcnt(0)
	s_setprio 1
	s_barrier
	v_mfma_f32_16x16x32_bf16 v[126:129], v[138:141], v[172:175], v[126:129]
	v_mfma_f32_16x16x32_bf16 v[122:125], v[148:151], v[172:175], v[122:125]
	v_mfma_f32_16x16x32_bf16 v[110:113], v[138:141], v[180:183], v[110:113]
	v_mfma_f32_16x16x32_bf16 v[106:109], v[148:151], v[180:183], v[106:109]
	v_mfma_f32_16x16x32_bf16 v[94:97], v[138:141], v[188:191], v[94:97]
	v_mfma_f32_16x16x32_bf16 v[90:93], v[148:151], v[188:191], v[90:93]
	v_mfma_f32_16x16x32_bf16 v[78:81], v[138:141], v[196:199], v[78:81]
	v_mfma_f32_16x16x32_bf16 v[74:77], v[148:151], v[196:199], v[74:77]
	v_mfma_f32_16x16x32_bf16 v[126:129], v[142:145], v[176:179], v[126:129]
	v_mfma_f32_16x16x32_bf16 v[122:125], v[152:155], v[176:179], v[122:125]
	v_mfma_f32_16x16x32_bf16 v[110:113], v[142:145], v[184:187], v[110:113]
	v_mfma_f32_16x16x32_bf16 v[106:109], v[152:155], v[184:187], v[106:109]
	v_mfma_f32_16x16x32_bf16 v[94:97], v[142:145], v[192:195], v[94:97]
	v_mfma_f32_16x16x32_bf16 v[90:93], v[152:155], v[192:195], v[90:93]
	v_mfma_f32_16x16x32_bf16 v[78:81], v[142:145], v[200:203], v[78:81]
	v_mfma_f32_16x16x32_bf16 v[74:77], v[152:155], v[200:203], v[74:77]
	v_mfma_f32_16x16x32_bf16 v[118:121], v[156:159], v[172:175], v[118:121]
	v_mfma_f32_16x16x32_bf16 v[114:117], v[164:167], v[172:175], v[114:117]
	v_mfma_f32_16x16x32_bf16 v[102:105], v[156:159], v[180:183], v[102:105]
	v_mfma_f32_16x16x32_bf16 v[98:101], v[164:167], v[180:183], v[98:101]
	v_mfma_f32_16x16x32_bf16 v[86:89], v[156:159], v[188:191], v[86:89]
	v_mfma_f32_16x16x32_bf16 v[82:85], v[164:167], v[188:191], v[82:85]
	v_mfma_f32_16x16x32_bf16 v[70:73], v[156:159], v[196:199], v[70:73]
	v_mfma_f32_16x16x32_bf16 v[66:69], v[164:167], v[196:199], v[66:69]
	v_mfma_f32_16x16x32_bf16 v[118:121], v[160:163], v[176:179], v[118:121]
	v_mfma_f32_16x16x32_bf16 v[114:117], v[168:171], v[176:179], v[114:117]
	v_mfma_f32_16x16x32_bf16 v[102:105], v[160:163], v[184:187], v[102:105]
	v_mfma_f32_16x16x32_bf16 v[98:101], v[168:171], v[184:187], v[98:101]
	v_mfma_f32_16x16x32_bf16 v[86:89], v[160:163], v[192:195], v[86:89]
	v_mfma_f32_16x16x32_bf16 v[82:85], v[168:171], v[192:195], v[82:85]
	v_mfma_f32_16x16x32_bf16 v[70:73], v[160:163], v[200:203], v[70:73]
	v_mfma_f32_16x16x32_bf16 v[66:69], v[168:171], v[200:203], v[66:69]
	s_barrier
	s_setprio 0
	s_mov_b32 m0, s65
	v_lshl_add_u64 v[204:205], v[204:205], 0, s[66:67]
	s_add_u32 s12, s12, 0x80080
	s_addc_u32 s13, s13, 0
	ds_read_b128 v[172:175], v147 offset:49152
	ds_read_b128 v[176:179], v147 offset:50176
	ds_read_b128 v[180:183], v147 offset:51200
	ds_read_b128 v[184:187], v147 offset:52224
	ds_read_b128 v[188:191], v147 offset:53248
	ds_read_b128 v[192:195], v147 offset:54272
	ds_read_b128 v[196:199], v147 offset:55296
	ds_read_b128 v[200:203], v147 offset:56320
	s_cmp_lg_u32 s100, 0
	s_cbranch_scc1 .Ltl_ia_2s
	global_load_lds_dwordx4 v[204:205], off
	v_lshl_add_u64 v[204:205], v[206:207], 0, s[66:67]
	s_mov_b32 m0, s68
	s_nop 0
	global_load_lds_dwordx4 v[204:205], off
	s_mov_b32 m0, s72
	s_nop 0
	global_load_lds_dwordx4 v130, s[12:13]
	s_mov_b32 m0, s73
	s_nop 0
	global_load_lds_dwordx4 v132, s[12:13]
	v_lshl_add_u64 v[204:205], v[208:209], 0, s[66:67]
	s_mov_b32 m0, s69
	s_nop 0
	global_load_lds_dwordx4 v[204:205], off
	v_lshl_add_u64 v[204:205], v[210:211], 0, s[66:67]
	s_mov_b32 m0, s70
	s_nop 0
	global_load_lds_dwordx4 v[204:205], off
	s_waitcnt vmcnt(8)
	s_branch .Ltl_ia_2d

; #define PG8_MMA(ai, bj, At, Bt) do { __builtin_amdgcn_s_setprio(1); _Pragma("unroll") for (int m = 0; m < NM; ++m) _Pragma("unroll") for (int n = 0; n < 2; ++n) _Pragma("unroll") for (int k = 0; k < 2; ++k) \
;         acc[ai][bj][m][n] = __builtin_amdgcn_mfma_f32_16x16x32_bf16(Bt[n][k], At[m][k], acc[ai][bj][m][n], 0, 0, 0); __builtin_amdgcn_s_setprio(0); } while (0)
; #define PG8_WAIT_V(n) asm volatile("s_waitcnt vmcnt(" #n ")" ::: "memory")
; #define PG8_WAIT_L(n) asm volatile("s_waitcnt lgkmcnt(" #n ")" ::: "memory")
; #define PG8_BAR __builtin_amdgcn_s_barrier()
; #define PG8_SCHED __builtin_amdgcn_sched_barrier(0)
;     ...
;             PG8_WAIT_V(8); PG8_WAIT_L(0); PG8_BAR; PG8_MMA(1, 0, At, B0); PG8_MMA(1, 1, At, B1); PG8_BAR; PG8_SCHED;
;     ...
;         }
;         if constexpr (ALIGN_EPI) { if (wr == 0) PG8_BAR; }
.Ltl_ia_2d:
	s_waitcnt lgkmcnt(0)
	s_setprio 1
	s_barrier
	v_mfma_f32_16x16x32_bf16 v[62:65], v[138:141], v[172:175], v[62:65]
	v_mfma_f32_16x16x32_bf16 v[58:61], v[148:151], v[172:175], v[58:61]
	v_mfma_f32_16x16x32_bf16 v[46:49], v[138:141], v[180:183], v[46:49]
	v_mfma_f32_16x16x32_bf16 v[42:45], v[148:151], v[180:183], v[42:45]
	v_mfma_f32_16x16x32_bf16 v[30:33], v[138:141], v[188:191], v[30:33]
	v_mfma_f32_16x16x32_bf16 v[26:29], v[148:151], v[188:191], v[26:29]
	v_mfma_f32_16x16x32_bf16 v[14:17], v[138:141], v[196:199], v[14:17]
	v_mfma_f32_16x16x32_bf16 v[10:13], v[148:151], v[196:199], v[10:13]
	v_mfma_f32_16x16x32_bf16 v[62:65], v[142:145], v[176:179], v[62:65]
	v_mfma_f32_16x16x32_bf16 v[58:61], v[152:155], v[176:179], v[58:61]
	v_mfma_f32_16x16x32_bf16 v[46:49], v[142:145], v[184:187], v[46:49]
	v_mfma_f32_16x16x32_bf16 v[42:45], v[152:155], v[184:187], v[42:45]
	v_mfma_f32_16x16x32_bf16 v[30:33], v[142:145], v[192:195], v[30:33]
	v_mfma_f32_16x16x32_bf16 v[26:29], v[152:155], v[192:195], v[26:29]
	v_mfma_f32_16x16x32_bf16 v[14:17], v[142:145], v[200:203], v[14:17]
	v_mfma_f32_16x16x32_bf16 v[10:13], v[152:155], v[200:203], v[10:13]
	v_mfma_f32_16x16x32_bf16 v[54:57], v[156:159], v[172:175], v[54:57]
	v_mfma_f32_16x16x32_bf16 v[50:53], v[164:167], v[172:175], v[50:53]
	v_mfma_f32_16x16x32_bf16 v[38:41], v[156:159], v[180:183], v[38:41]
	v_mfma_f32_16x16x32_bf16 v[34:37], v[164:167], v[180:183], v[34:37]
	v_mfma_f32_16x16x32_bf16 v[22:25], v[156:159], v[188:191], v[22:25]
	v_mfma_f32_16x16x32_bf16 v[18:21], v[164:167], v[188:191], v[18:21]
	v_mfma_f32_16x16x32_bf16 v[6:9], v[156:159], v[196:199], v[6:9]
	v_mfma_f32_16x16x32_bf16 v[2:5], v[164:167], v[196:199], v[2:5]
	v_mfma_f32_16x16x32_bf16 v[54:57], v[160:163], v[176:179], v[54:57]
	v_mfma_f32_16x16x32_bf16 v[50:53], v[168:171], v[176:179], v[50:53]
	v_mfma_f32_16x16x32_bf16 v[38:41], v[160:163], v[184:187], v[38:41]
	v_mfma_f32_16x16x32_bf16 v[34:37], v[168:171], v[184:187], v[34:37]
	v_mfma_f32_16x16x32_bf16 v[22:25], v[160:163], v[192:195], v[22:25]
	v_mfma_f32_16x16x32_bf16 v[18:21], v[168:171], v[192:195], v[18:21]
	v_mfma_f32_16x16x32_bf16 v[6:9], v[160:163], v[200:203], v[6:9]
	v_mfma_f32_16x16x32_bf16 v[2:5], v[168:171], v[200:203], v[2:5]
	s_barrier
	s_setprio 0
	s_add_i32 s39, s39, 2
	s_add_u32 s10, s10, 0x100
	s_addc_u32 s11, s11, 0
	s_add_u32 s29, s29, 0x100
	s_addc_u32 s38, s38, 0
	s_cmp_gt_u32 s39, 29
	s_cbranch_scc0 .LBB0_703
	s_and_b64 vcc, exec, s[18:19]
	s_cbranch_vccz .LBB0_706
	s_barrier

; #define PG8_STAGE(bufoff, gbase, voff) do { _Pragma("unroll") for (int _i = 0; _i < 2; ++_i) \
;         __builtin_amdgcn_global_load_lds((const unsigned*)((const char*)(gbase) + (voff)[_i]), (LAS unsigned*)(lds + (bufoff) + ldsw + _i * 8192), 16, 0, 0); } while (0)
; #define PG8_LDA(dst, b, h) do { _Pragma("unroll") for (int m = 0; m < NM; ++m) _Pragma("unroll") for (int k = 0; k < 2; ++k) dst[m][k] = *(const LAS bf16x8*)(lds + PG8_SA(b, h) + aoff + m * 2048 + k * 1024); } while (0)
; #define PG8_LDB(dst, b, h) do { _Pragma("unroll") for (int n = 0; n < 2; ++n) _Pragma("unroll") for (int k = 0; k < 2; ++k) dst[n][k] = *(const LAS bf16x8*)(lds + PG8_SB(b, h) + boff + n * 2048 + k * 1024); } while (0)
; #define PG8_MMA(ai, bj, At, Bt) do { __builtin_amdgcn_s_setprio(1); _Pragma("unroll") for (int m = 0; m < NM; ++m) _Pragma("unroll") for (int n = 0; n < 2; ++n) _Pragma("unroll") for (int k = 0; k < 2; ++k) \
;         acc[ai][bj][m][n] = __builtin_amdgcn_mfma_f32_16x16x32_bf16(Bt[n][k], At[m][k], acc[ai][bj][m][n], 0, 0, 0); __builtin_amdgcn_s_setprio(0); } while (0)
; #define PG8_WAIT_V(n) asm volatile("s_waitcnt vmcnt(" #n ")" ::: "memory")
; #define PG8_WAIT_L(n) asm volatile("s_waitcnt lgkmcnt(" #n ")" ::: "memory")
; #define PG8_BAR __builtin_amdgcn_s_barrier()
; #define PG8_SCHED __builtin_amdgcn_sched_barrier(0)
;     ...
;         for (int t = 0; t < nt; t += 2) {
;             const bool last = (t == nt - 2);
;             const char* a1 = cA + (size_t)(t + 1) * kstep;
;             const char* a2 = last ? nA : cA + (size_t)(t + 2) * kstep; const char* b2 = last ? nB : cB + (size_t)(t + 2) * kstep;
;             const char* a3 = a2 + kstep; const char* b3 = b2 + kstep;
;             if constexpr (SP2) {
;             PG8_LDB(B0, 0, 0); PG8_LDB(B1, 0, 1); PG8_SCHED; PG8_LDA(At, 0, 0); PG8_STAGE(PG8_SA(1, 1), a1 + hstepA, voffA);
;             PG8_WAIT_V(8); PG8_WAIT_L(0); PG8_BAR; PG8_MMA(0, 0, At, B0); PG8_MMA(0, 1, At, B1); PG8_BAR; PG8_SCHED;
;             PG8_LDA(At, 0, 1); PG8_STAGE(PG8_SB(0, 0), b2, voffB); PG8_STAGE(PG8_SB(0, 1), b2 + hstepB, voffB); PG8_STAGE(PG8_SA(0, 0), a2, voffA);
.LBB0_1192:
	v_add_u32_e32 v0, s49, v216
	ds_read_b128 v[10:13], v0
	ds_read_b128 v[14:17], v0 offset:1024
	ds_read_b128 v[18:21], v0 offset:2048
	ds_read_b128 v[22:25], v0 offset:3072
	v_add_u32_e32 v0, s58, v216
	ds_read_b128 v[26:29], v0
	ds_read_b128 v[30:33], v0 offset:1024
	ds_read_b128 v[42:45], v0 offset:2048
	ds_read_b128 v[46:49], v0 offset:3072
	s_add_u32 s12, s10, 0xfffe0080
	s_addc_u32 s13, s11, -1
	s_cmp_eq_u32 s54, 4
	s_cselect_b32 s35, s2, s13
	s_cselect_b32 s34, s3, s12
	s_cselect_b32 s13, s7, s52
	s_cselect_b32 s12, s27, s9
	s_cselect_b32 s100, -1, 0
	s_andn2_b32 s100, s100, s101
	s_add_i32 m0, s62, 0xc000
	ds_read_b128 v[50:53], v217
	ds_read_b128 v[54:57], v217 offset:1024
	ds_read_b128 v[58:61], v217 offset:2048
	ds_read_b128 v[62:65], v217 offset:3072
	ds_read_b128 v[178:181], v217 offset:4096
	ds_read_b128 v[182:185], v217 offset:5120
	ds_read_b128 v[198:201], v217 offset:6144
	ds_read_b128 v[208:211], v217 offset:7168
	global_load_lds_dwordx4 v194, s[10:11]
	s_add_i32 m0, s62, 0xe000
	s_nop 0
	global_load_lds_dwordx4 v196, s[10:11]
	s_waitcnt vmcnt(8)
	s_waitcnt lgkmcnt(0)
	s_setprio 1
	s_barrier
	v_mfma_f32_16x16x32_bf16 v[38:41], v[10:13], v[50:53], v[38:41]
	v_mfma_f32_16x16x32_bf16 v[34:37], v[18:21], v[50:53], v[34:37]
	v_mfma_f32_16x16x32_bf16 v[174:177], v[10:13], v[58:61], v[174:177]
	v_mfma_f32_16x16x32_bf16 v[170:173], v[18:21], v[58:61], v[170:173]
	v_mfma_f32_16x16x32_bf16 v[158:161], v[10:13], v[178:181], v[158:161]
	v_mfma_f32_16x16x32_bf16 v[154:157], v[18:21], v[178:181], v[154:157]
	v_mfma_f32_16x16x32_bf16 v[142:145], v[10:13], v[198:201], v[142:145]
	v_mfma_f32_16x16x32_bf16 v[138:141], v[18:21], v[198:201], v[138:141]
	v_mfma_f32_16x16x32_bf16 v[38:41], v[14:17], v[54:57], v[38:41]
	v_mfma_f32_16x16x32_bf16 v[34:37], v[22:25], v[54:57], v[34:37]
	v_mfma_f32_16x16x32_bf16 v[174:177], v[14:17], v[62:65], v[174:177]
	v_mfma_f32_16x16x32_bf16 v[170:173], v[22:25], v[62:65], v[170:173]
	v_mfma_f32_16x16x32_bf16 v[158:161], v[14:17], v[182:185], v[158:161]
	v_mfma_f32_16x16x32_bf16 v[154:157], v[22:25], v[182:185], v[154:157]
	v_mfma_f32_16x16x32_bf16 v[142:145], v[14:17], v[208:211], v[142:145]
	v_mfma_f32_16x16x32_bf16 v[138:141], v[22:25], v[208:211], v[138:141]
	v_mfma_f32_16x16x32_bf16 v[6:9], v[26:29], v[50:53], v[6:9]
	v_mfma_f32_16x16x32_bf16 v[2:5], v[42:45], v[50:53], v[2:5]
	v_mfma_f32_16x16x32_bf16 v[6:9], v[30:33], v[54:57], v[6:9]
	v_mfma_f32_16x16x32_bf16 v[2:5], v[46:49], v[54:57], v[2:5]
	v_mfma_f32_16x16x32_bf16 v[50:53], v[26:29], v[58:61], v[166:169]
	v_mfma_f32_16x16x32_bf16 v[54:57], v[42:45], v[58:61], v[162:165]
	v_mfma_f32_16x16x32_bf16 v[134:137], v[26:29], v[198:201], v[134:137]
	v_mfma_f32_16x16x32_bf16 v[130:133], v[42:45], v[198:201], v[130:133]
	v_mfma_f32_16x16x32_bf16 v[50:53], v[30:33], v[62:65], v[50:53]
	v_mfma_f32_16x16x32_bf16 v[54:57], v[46:49], v[62:65], v[54:57]
	v_mfma_f32_16x16x32_bf16 v[58:61], v[26:29], v[178:181], v[150:153]
	v_mfma_f32_16x16x32_bf16 v[62:65], v[42:45], v[178:181], v[146:149]
	v_mfma_f32_16x16x32_bf16 v[134:137], v[30:33], v[208:211], v[134:137]
	v_mfma_f32_16x16x32_bf16 v[130:133], v[46:49], v[208:211], v[130:133]
	v_mfma_f32_16x16x32_bf16 v[58:61], v[30:33], v[182:185], v[58:61]
	v_mfma_f32_16x16x32_bf16 v[62:65], v[46:49], v[182:185], v[62:65]
	s_barrier
	s_setprio 0
	s_mov_b32 m0, s50
	v_lshl_add_u64 v[202:203], s[12:13], 0, v[188:189]
	s_add_u32 s56, s12, 0x20000
	s_addc_u32 s57, s13, 0
	ds_read_b128 v[146:149], v217 offset:16384
	ds_read_b128 v[150:153], v217 offset:17408
	ds_read_b128 v[162:165], v217 offset:18432
	ds_read_b128 v[166:169], v217 offset:19456
	ds_read_b128 v[178:181], v217 offset:20480
	ds_read_b128 v[182:185], v217 offset:21504
	ds_read_b128 v[198:201], v217 offset:22528
	ds_read_b128 v[208:211], v217 offset:23552
	s_cmp_lg_u32 s100, 0
	s_cbranch_scc1 .Ltl_qp_0s
	global_load_lds_dwordx4 v188, s[12:13]
	v_lshl_add_u64 v[204:205], s[12:13], 0, v[192:193]
	s_mov_b32 m0, s51
	s_nop 0
	global_load_lds_dwordx4 v192, s[12:13]
	s_mov_b32 m0, s59
	v_lshl_add_u64 v[222:223], s[34:35], 0, v[190:191]
	global_load_lds_dwordx4 v188, s[56:57]
	s_mov_b32 m0, s60
	s_nop 0
	global_load_lds_dwordx4 v192, s[56:57]
	v_lshl_add_u64 v[206:207], s[34:35], 0, v[186:187]
	s_mov_b32 m0, s62
	s_nop 0
	global_load_lds_dwordx4 v186, s[34:35]
	s_mov_b32 m0, s63
	s_nop 0
	global_load_lds_dwordx4 v190, s[34:35]
	s_waitcnt vmcnt(8)
	s_branch .Ltl_qp_0d

; #define PG8_STAGE(bufoff, gbase, voff) do { _Pragma("unroll") for (int _i = 0; _i < 2; ++_i) \
;         __builtin_amdgcn_global_load_lds((const unsigned*)((const char*)(gbase) + (voff)[_i]), (LAS unsigned*)(lds + (bufoff) + ldsw + _i * 8192), 16, 0, 0); } while (0)
; #define PG8_LDA(dst, b, h) do { _Pragma("unroll") for (int m = 0; m < NM; ++m) _Pragma("unroll") for (int k = 0; k < 2; ++k) dst[m][k] = *(const LAS bf16x8*)(lds + PG8_SA(b, h) + aoff + m * 2048 + k * 1024); } while (0)
; #define PG8_LDB(dst, b, h) do { _Pragma("unroll") for (int n = 0; n < 2; ++n) _Pragma("unroll") for (int k = 0; k < 2; ++k) dst[n][k] = *(const LAS bf16x8*)(lds + PG8_SB(b, h) + boff + n * 2048 + k * 1024); } while (0)
; #define PG8_MMA(ai, bj, At, Bt) do { __builtin_amdgcn_s_setprio(1); _Pragma("unroll") for (int m = 0; m < NM; ++m) _Pragma("unroll") for (int n = 0; n < 2; ++n) _Pragma("unroll") for (int k = 0; k < 2; ++k) \
;         acc[ai][bj][m][n] = __builtin_amdgcn_mfma_f32_16x16x32_bf16(Bt[n][k], At[m][k], acc[ai][bj][m][n], 0, 0, 0); __builtin_amdgcn_s_setprio(0); } while (0)
; #define PG8_WAIT_V(n) asm volatile("s_waitcnt vmcnt(" #n ")" ::: "memory")
; #define PG8_WAIT_L(n) asm volatile("s_waitcnt lgkmcnt(" #n ")" ::: "memory")
; #define PG8_BAR __builtin_amdgcn_s_barrier()
; #define PG8_SCHED __builtin_amdgcn_sched_barrier(0)
;     ...
;             PG8_WAIT_V(8); PG8_WAIT_L(0); PG8_BAR; PG8_MMA(1, 0, At, B0); PG8_MMA(1, 1, At, B1); PG8_BAR; PG8_SCHED;
;             PG8_LDB(B0, 1, 0); PG8_LDB(B1, 1, 1); PG8_SCHED; PG8_LDA(At, 1, 0); PG8_STAGE(PG8_SA(0, 1), a2 + hstepA, voffA);
.Ltl_qp_0d:
	s_waitcnt lgkmcnt(0)
	s_setprio 1
	s_barrier
	v_mfma_f32_16x16x32_bf16 v[126:129], v[10:13], v[146:149], v[126:129]
	v_mfma_f32_16x16x32_bf16 v[122:125], v[18:21], v[146:149], v[122:125]
	v_mfma_f32_16x16x32_bf16 v[110:113], v[10:13], v[162:165], v[110:113]
	v_mfma_f32_16x16x32_bf16 v[106:109], v[18:21], v[162:165], v[106:109]
	v_mfma_f32_16x16x32_bf16 v[94:97], v[10:13], v[178:181], v[94:97]
	v_mfma_f32_16x16x32_bf16 v[90:93], v[18:21], v[178:181], v[90:93]
	v_mfma_f32_16x16x32_bf16 v[10:13], v[10:13], v[198:201], v[78:81]
	v_mfma_f32_16x16x32_bf16 v[126:129], v[14:17], v[150:153], v[126:129]
	v_mfma_f32_16x16x32_bf16 v[122:125], v[22:25], v[150:153], v[122:125]
	v_mfma_f32_16x16x32_bf16 v[110:113], v[14:17], v[166:169], v[110:113]
	v_mfma_f32_16x16x32_bf16 v[106:109], v[22:25], v[166:169], v[106:109]
	v_mfma_f32_16x16x32_bf16 v[94:97], v[14:17], v[182:185], v[94:97]
	v_mfma_f32_16x16x32_bf16 v[90:93], v[22:25], v[182:185], v[90:93]
	v_mfma_f32_16x16x32_bf16 v[10:13], v[14:17], v[208:211], v[10:13]
	v_mfma_f32_16x16x32_bf16 v[14:17], v[18:21], v[198:201], v[74:77]
	v_mfma_f32_16x16x32_bf16 v[14:17], v[22:25], v[208:211], v[14:17]
	v_mfma_f32_16x16x32_bf16 v[74:77], v[26:29], v[162:165], v[102:105]
	v_mfma_f32_16x16x32_bf16 v[102:105], v[30:33], v[166:169], v[74:77]
	v_mfma_f32_16x16x32_bf16 v[74:77], v[42:45], v[162:165], v[98:101]
	v_mfma_f32_16x16x32_bf16 v[98:101], v[46:49], v[166:169], v[74:77]
	v_mfma_f32_16x16x32_bf16 v[74:77], v[26:29], v[178:181], v[86:89]
	v_mfma_f32_16x16x32_bf16 v[18:21], v[26:29], v[146:149], v[118:121]
	v_mfma_f32_16x16x32_bf16 v[86:89], v[30:33], v[182:185], v[74:77]
	v_mfma_f32_16x16x32_bf16 v[74:77], v[42:45], v[178:181], v[82:85]
	v_mfma_f32_16x16x32_bf16 v[26:29], v[26:29], v[198:201], v[70:73]
	v_mfma_f32_16x16x32_bf16 v[18:21], v[30:33], v[150:153], v[18:21]
	v_mfma_f32_16x16x32_bf16 v[22:25], v[42:45], v[146:149], v[114:117]
	v_mfma_f32_16x16x32_bf16 v[82:85], v[46:49], v[182:185], v[74:77]
	v_mfma_f32_16x16x32_bf16 v[26:29], v[30:33], v[208:211], v[26:29]
	v_mfma_f32_16x16x32_bf16 v[30:33], v[42:45], v[198:201], v[66:69]
	v_mfma_f32_16x16x32_bf16 v[22:25], v[46:49], v[150:153], v[22:25]
	v_mfma_f32_16x16x32_bf16 v[30:33], v[46:49], v[208:211], v[30:33]
	s_barrier
	s_setprio 0
	v_add_u32_e32 v0, s69, v216
	ds_read_b128 v[42:45], v0
	ds_read_b128 v[46:49], v0 offset:1024
	ds_read_b128 v[66:69], v0 offset:2048
	ds_read_b128 v[70:73], v0 offset:3072
	v_add_u32_e32 v0, s74, v216
	ds_read_b128 v[178:181], v0
	ds_read_b128 v[182:185], v0 offset:1024
	ds_read_b128 v[198:201], v0 offset:2048
	ds_read_b128 v[208:211], v0 offset:3072
	s_add_u32 s34, s34, 0x20000
	s_addc_u32 s35, s35, 0
	s_mov_b32 m0, s64
	ds_read_b128 v[74:77], v217 offset:32768
	ds_read_b128 v[78:81], v217 offset:33792
	ds_read_b128 v[114:117], v217 offset:34816
	ds_read_b128 v[118:121], v217 offset:35840
	ds_read_b128 v[146:149], v217 offset:36864
	ds_read_b128 v[212:215], v217 offset:37888
	ds_read_b128 v[218:221], v217 offset:38912
	ds_read_b128 v[226:229], v217 offset:39936
	s_cmp_lg_u32 s100, 0
	s_cbranch_scc1 .Ltl_qp_1s
	global_load_lds_dwordx4 v186, s[34:35]
	s_mov_b32 m0, s68
	s_nop 0
	global_load_lds_dwordx4 v190, s[34:35]
	s_waitcnt vmcnt(8)
	s_branch .Ltl_qp_1d

; #define PG8_STAGE(bufoff, gbase, voff) do { _Pragma("unroll") for (int _i = 0; _i < 2; ++_i) \
;         __builtin_amdgcn_global_load_lds((const unsigned*)((const char*)(gbase) + (voff)[_i]), (LAS unsigned*)(lds + (bufoff) + ldsw + _i * 8192), 16, 0, 0); } while (0)
; #define PG8_LDA(dst, b, h) do { _Pragma("unroll") for (int m = 0; m < NM; ++m) _Pragma("unroll") for (int k = 0; k < 2; ++k) dst[m][k] = *(const LAS bf16x8*)(lds + PG8_SA(b, h) + aoff + m * 2048 + k * 1024); } while (0)
; #define PG8_MMA(ai, bj, At, Bt) do { __builtin_amdgcn_s_setprio(1); _Pragma("unroll") for (int m = 0; m < NM; ++m) _Pragma("unroll") for (int n = 0; n < 2; ++n) _Pragma("unroll") for (int k = 0; k < 2; ++k) \
;         acc[ai][bj][m][n] = __builtin_amdgcn_mfma_f32_16x16x32_bf16(Bt[n][k], At[m][k], acc[ai][bj][m][n], 0, 0, 0); __builtin_amdgcn_s_setprio(0); } while (0)
; #define PG8_WAIT_V(n) asm volatile("s_waitcnt vmcnt(" #n ")" ::: "memory")
; #define PG8_WAIT_L(n) asm volatile("s_waitcnt lgkmcnt(" #n ")" ::: "memory")
; #define PG8_BAR __builtin_amdgcn_s_barrier()
; #define PG8_SCHED __builtin_amdgcn_sched_barrier(0)
;     ...
;             PG8_WAIT_V(8); PG8_WAIT_L(0); PG8_BAR; PG8_MMA(0, 0, At, B0); PG8_MMA(0, 1, At, B1); PG8_BAR; PG8_SCHED;
;             PG8_LDA(At, 1, 1); PG8_STAGE(PG8_SB(1, 0), b3, voffB); PG8_STAGE(PG8_SB(1, 1), b3 + hstepB, voffB); PG8_STAGE(PG8_SA(1, 0), a3, voffA);
.Ltl_qp_1d:
	s_waitcnt lgkmcnt(0)
	s_setprio 1
	s_barrier
	v_mfma_f32_16x16x32_bf16 v[150:153], v[42:45], v[114:117], v[174:177]
	v_mfma_f32_16x16x32_bf16 v[174:177], v[46:49], v[118:121], v[150:153]
	v_mfma_f32_16x16x32_bf16 v[150:153], v[66:69], v[114:117], v[170:173]
	v_mfma_f32_16x16x32_bf16 v[170:173], v[70:73], v[118:121], v[150:153]
	v_mfma_f32_16x16x32_bf16 v[150:153], v[42:45], v[146:149], v[158:161]
	v_mfma_f32_16x16x32_bf16 v[38:41], v[42:45], v[74:77], v[38:41]
	v_mfma_f32_16x16x32_bf16 v[34:37], v[66:69], v[74:77], v[34:37]
	v_mfma_f32_16x16x32_bf16 v[158:161], v[46:49], v[212:215], v[150:153]
	v_mfma_f32_16x16x32_bf16 v[150:153], v[66:69], v[146:149], v[154:157]
	v_mfma_f32_16x16x32_bf16 v[142:145], v[42:45], v[218:221], v[142:145]
	v_mfma_f32_16x16x32_bf16 v[138:141], v[66:69], v[218:221], v[138:141]
	v_mfma_f32_16x16x32_bf16 v[38:41], v[46:49], v[78:81], v[38:41]
	v_mfma_f32_16x16x32_bf16 v[34:37], v[70:73], v[78:81], v[34:37]
	v_mfma_f32_16x16x32_bf16 v[154:157], v[70:73], v[212:215], v[150:153]
	v_mfma_f32_16x16x32_bf16 v[142:145], v[46:49], v[226:229], v[142:145]
	v_mfma_f32_16x16x32_bf16 v[138:141], v[70:73], v[226:229], v[138:141]
	v_mfma_f32_16x16x32_bf16 v[50:53], v[178:181], v[114:117], v[50:53]
	v_mfma_f32_16x16x32_bf16 v[166:169], v[182:185], v[118:121], v[50:53]
	v_mfma_f32_16x16x32_bf16 v[50:53], v[198:201], v[114:117], v[54:57]
	v_mfma_f32_16x16x32_bf16 v[162:165], v[208:211], v[118:121], v[50:53]
	v_mfma_f32_16x16x32_bf16 v[50:53], v[178:181], v[146:149], v[58:61]
	v_mfma_f32_16x16x32_bf16 v[150:153], v[182:185], v[212:215], v[50:53]
	v_mfma_f32_16x16x32_bf16 v[50:53], v[198:201], v[146:149], v[62:65]
	v_mfma_f32_16x16x32_bf16 v[146:149], v[208:211], v[212:215], v[50:53]
	v_mfma_f32_16x16x32_bf16 v[50:53], v[178:181], v[218:221], v[134:137]
	v_mfma_f32_16x16x32_bf16 v[6:9], v[178:181], v[74:77], v[6:9]
	v_mfma_f32_16x16x32_bf16 v[2:5], v[198:201], v[74:77], v[2:5]
	v_mfma_f32_16x16x32_bf16 v[134:137], v[182:185], v[226:229], v[50:53]
	v_mfma_f32_16x16x32_bf16 v[50:53], v[198:201], v[218:221], v[130:133]
	v_mfma_f32_16x16x32_bf16 v[6:9], v[182:185], v[78:81], v[6:9]
	v_mfma_f32_16x16x32_bf16 v[2:5], v[208:211], v[78:81], v[2:5]
	v_mfma_f32_16x16x32_bf16 v[130:133], v[208:211], v[226:229], v[50:53]
	s_barrier
	s_setprio 0
	s_mov_b32 m0, s70
	v_lshl_add_u64 v[74:75], v[202:203], 0, s[66:67]
	s_add_u32 s12, s12, 0x20080
	s_addc_u32 s13, s13, 0
	ds_read_b128 v[50:53], v217 offset:49152
	ds_read_b128 v[54:57], v217 offset:50176
	ds_read_b128 v[58:61], v217 offset:51200
	ds_read_b128 v[62:65], v217 offset:52224
	ds_read_b128 v[212:215], v217 offset:53248
	ds_read_b128 v[218:221], v217 offset:54272
	ds_read_b128 v[226:229], v217 offset:55296
	ds_read_b128 v[230:233], v217 offset:56320
	s_cmp_lg_u32 s100, 0
	s_cbranch_scc1 .Ltl_qp_2s
	global_load_lds_dwordx4 v[74:75], off
	v_lshl_add_u64 v[74:75], v[204:205], 0, s[66:67]
	s_mov_b32 m0, s71
	s_nop 0
	global_load_lds_dwordx4 v[74:75], off
	s_mov_b32 m0, s75
	s_nop 0
	global_load_lds_dwordx4 v188, s[12:13]
	s_mov_b32 m0, s80
	s_nop 0
	global_load_lds_dwordx4 v192, s[12:13]
	v_lshl_add_u64 v[74:75], v[206:207], 0, s[66:67]
	s_mov_b32 m0, s72
	s_nop 0
	global_load_lds_dwordx4 v[74:75], off
	v_lshl_add_u64 v[74:75], v[222:223], 0, s[66:67]
	s_mov_b32 m0, s73
	s_nop 0
	global_load_lds_dwordx4 v[74:75], off
	s_waitcnt vmcnt(8)
	s_branch .Ltl_qp_2d

; #define PG8_MMA(ai, bj, At, Bt) do { __builtin_amdgcn_s_setprio(1); _Pragma("unroll") for (int m = 0; m < NM; ++m) _Pragma("unroll") for (int n = 0; n < 2; ++n) _Pragma("unroll") for (int k = 0; k < 2; ++k) \
;         acc[ai][bj][m][n] = __builtin_amdgcn_mfma_f32_16x16x32_bf16(Bt[n][k], At[m][k], acc[ai][bj][m][n], 0, 0, 0); __builtin_amdgcn_s_setprio(0); } while (0)
; #define PG8_WAIT_V(n) asm volatile("s_waitcnt vmcnt(" #n ")" ::: "memory")
; #define PG8_WAIT_L(n) asm volatile("s_waitcnt lgkmcnt(" #n ")" ::: "memory")
; #define PG8_BAR __builtin_amdgcn_s_barrier()
; #define PG8_SCHED __builtin_amdgcn_sched_barrier(0)
;     ...
;             PG8_WAIT_V(8); PG8_WAIT_L(0); PG8_BAR; PG8_MMA(1, 0, At, B0); PG8_MMA(1, 1, At, B1); PG8_BAR; PG8_SCHED;
;     ...
;         }
;         if constexpr (ALIGN_EPI) { if (wr == 0) PG8_BAR; }
.Ltl_qp_2d:
	s_waitcnt lgkmcnt(0)
	s_setprio 1
	s_barrier
	v_mfma_f32_16x16x32_bf16 v[74:77], v[42:45], v[50:53], v[126:129]
	v_mfma_f32_16x16x32_bf16 v[126:129], v[46:49], v[54:57], v[74:77]
	v_mfma_f32_16x16x32_bf16 v[74:77], v[66:69], v[50:53], v[122:125]
	v_mfma_f32_16x16x32_bf16 v[122:125], v[70:73], v[54:57], v[74:77]
	v_mfma_f32_16x16x32_bf16 v[74:77], v[42:45], v[58:61], v[110:113]
	v_mfma_f32_16x16x32_bf16 v[110:113], v[46:49], v[62:65], v[74:77]
	v_mfma_f32_16x16x32_bf16 v[74:77], v[66:69], v[58:61], v[106:109]
	v_mfma_f32_16x16x32_bf16 v[106:109], v[70:73], v[62:65], v[74:77]
	v_mfma_f32_16x16x32_bf16 v[74:77], v[42:45], v[212:215], v[94:97]
	v_mfma_f32_16x16x32_bf16 v[10:13], v[42:45], v[226:229], v[10:13]
	v_mfma_f32_16x16x32_bf16 v[94:97], v[46:49], v[218:221], v[74:77]
	v_mfma_f32_16x16x32_bf16 v[74:77], v[66:69], v[212:215], v[90:93]
	v_mfma_f32_16x16x32_bf16 v[78:81], v[46:49], v[230:233], v[10:13]
	v_mfma_f32_16x16x32_bf16 v[10:13], v[66:69], v[226:229], v[14:17]
	v_mfma_f32_16x16x32_bf16 v[90:93], v[70:73], v[218:221], v[74:77]
	v_mfma_f32_16x16x32_bf16 v[74:77], v[70:73], v[230:233], v[10:13]
	v_mfma_f32_16x16x32_bf16 v[10:13], v[178:181], v[50:53], v[18:21]
	v_mfma_f32_16x16x32_bf16 v[118:121], v[182:185], v[54:57], v[10:13]
	v_mfma_f32_16x16x32_bf16 v[10:13], v[198:201], v[50:53], v[22:25]
	v_mfma_f32_16x16x32_bf16 v[114:117], v[208:211], v[54:57], v[10:13]
	v_mfma_f32_16x16x32_bf16 v[10:13], v[178:181], v[58:61], v[102:105]
	v_mfma_f32_16x16x32_bf16 v[102:105], v[182:185], v[62:65], v[10:13]
	v_mfma_f32_16x16x32_bf16 v[10:13], v[198:201], v[58:61], v[98:101]
	v_mfma_f32_16x16x32_bf16 v[98:101], v[208:211], v[62:65], v[10:13]
	v_mfma_f32_16x16x32_bf16 v[10:13], v[178:181], v[212:215], v[86:89]
	v_mfma_f32_16x16x32_bf16 v[86:89], v[182:185], v[218:221], v[10:13]
	v_mfma_f32_16x16x32_bf16 v[10:13], v[198:201], v[212:215], v[82:85]
	v_mfma_f32_16x16x32_bf16 v[82:85], v[208:211], v[218:221], v[10:13]
	v_mfma_f32_16x16x32_bf16 v[10:13], v[178:181], v[226:229], v[26:29]
	v_mfma_f32_16x16x32_bf16 v[70:73], v[182:185], v[230:233], v[10:13]
	v_mfma_f32_16x16x32_bf16 v[10:13], v[198:201], v[226:229], v[30:33]
	v_mfma_f32_16x16x32_bf16 v[66:69], v[208:211], v[230:233], v[10:13]
	s_barrier
	s_setprio 0
	s_add_i32 s54, s54, 2
	s_add_u32 s10, s10, 0x100
	s_addc_u32 s11, s11, 0
	s_add_u32 s9, s9, 0x100
	s_addc_u32 s52, s52, 0
	s_cmp_gt_u32 s54, 5
	s_cbranch_scc0 .LBB0_1192
	s_and_b64 vcc, exec, s[16:17]
	s_cbranch_vccz .LBB0_1195
	s_barrier

; #define PG8_STAGE(bufoff, gbase, voff) do { _Pragma("unroll") for (int _i = 0; _i < 2; ++_i) \
;         __builtin_amdgcn_global_load_lds((const unsigned*)((const char*)(gbase) + (voff)[_i]), (LAS unsigned*)(lds + (bufoff) + ldsw + _i * 8192), 16, 0, 0); } while (0)
; #define PG8_LDA(dst, b, h) do { _Pragma("unroll") for (int m = 0; m < NM; ++m) _Pragma("unroll") for (int k = 0; k < 2; ++k) dst[m][k] = *(const LAS bf16x8*)(lds + PG8_SA(b, h) + aoff + m * 2048 + k * 1024); } while (0)
; #define PG8_LDB(dst, b, h) do { _Pragma("unroll") for (int n = 0; n < 2; ++n) _Pragma("unroll") for (int k = 0; k < 2; ++k) dst[n][k] = *(const LAS bf16x8*)(lds + PG8_SB(b, h) + boff + n * 2048 + k * 1024); } while (0)
; #define PG8_MMA(ai, bj, At, Bt) do { __builtin_amdgcn_s_setprio(1); _Pragma("unroll") for (int m = 0; m < NM; ++m) _Pragma("unroll") for (int n = 0; n < 2; ++n) _Pragma("unroll") for (int k = 0; k < 2; ++k) \
;         acc[ai][bj][m][n] = __builtin_amdgcn_mfma_f32_16x16x32_bf16(Bt[n][k], At[m][k], acc[ai][bj][m][n], 0, 0, 0); __builtin_amdgcn_s_setprio(0); } while (0)
; #define PG8_WAIT_V(n) asm volatile("s_waitcnt vmcnt(" #n ")" ::: "memory")
; #define PG8_WAIT_L(n) asm volatile("s_waitcnt lgkmcnt(" #n ")" ::: "memory")
; #define PG8_BAR __builtin_amdgcn_s_barrier()
; #define PG8_SCHED __builtin_amdgcn_sched_barrier(0)
;     ...
;         for (int t = 0; t < nt; t += 2) {
;             const bool last = (t == nt - 2);
;             const char* a1 = cA + (size_t)(t + 1) * kstep;
;             const char* a2 = last ? nA : cA + (size_t)(t + 2) * kstep; const char* b2 = last ? nB : cB + (size_t)(t + 2) * kstep;
;             const char* a3 = a2 + kstep; const char* b3 = b2 + kstep;
;             if constexpr (SP2) {
;             PG8_LDB(B0, 0, 0); PG8_LDB(B1, 0, 1); PG8_SCHED; PG8_LDA(At, 0, 0); PG8_STAGE(PG8_SA(1, 1), a1 + hstepA, voffA);
;             PG8_WAIT_V(8); PG8_WAIT_L(0); PG8_BAR; PG8_MMA(0, 0, At, B0); PG8_MMA(0, 1, At, B1); PG8_BAR; PG8_SCHED;
;             PG8_LDA(At, 0, 1); PG8_STAGE(PG8_SB(0, 0), b2, voffB); PG8_STAGE(PG8_SB(0, 1), b2 + hstepB, voffB); PG8_STAGE(PG8_SA(0, 0), a2, voffA);
.LBB0_1454:
	v_add_u32_e32 v140, s31, v142
	ds_read_b128 v[144:147], v140
	ds_read_b128 v[148:151], v140 offset:1024
	ds_read_b128 v[152:155], v140 offset:2048
	ds_read_b128 v[156:159], v140 offset:3072
	v_add_u32_e32 v140, s35, v142
	ds_read_b128 v[160:163], v140
	ds_read_b128 v[164:167], v140 offset:1024
	ds_read_b128 v[168:171], v140 offset:2048
	ds_read_b128 v[172:175], v140 offset:3072
	s_add_u32 s6, s20, 0x100
	s_addc_u32 s7, s21, 0
	s_cmp_eq_u32 s73, 4
	s_cselect_b32 s25, s17, s7
	s_cselect_b32 s24, s16, s6
	s_cselect_b32 s23, s2, s60
	s_cselect_b32 s22, s3, s15
	s_cselect_b32 s100, -1, 0
	s_andn2_b32 s100, s100, s101
	s_add_i32 m0, s45, 0xc000
	ds_read_b128 v[176:179], v143
	ds_read_b128 v[180:183], v143 offset:1024
	ds_read_b128 v[184:187], v143 offset:2048
	ds_read_b128 v[188:191], v143 offset:3072
	ds_read_b128 v[192:195], v143 offset:4096
	ds_read_b128 v[196:199], v143 offset:5120
	ds_read_b128 v[200:203], v143 offset:6144
	ds_read_b128 v[208:211], v143 offset:7168
	global_load_lds_dwordx4 v136, s[20:21]
	s_add_i32 m0, s45, 0xe000
	s_nop 0
	global_load_lds_dwordx4 v138, s[20:21]
	s_waitcnt vmcnt(8)
	s_waitcnt lgkmcnt(0)
	s_setprio 1
	s_barrier
	v_mfma_f32_16x16x32_bf16 v[126:129], v[144:147], v[176:179], v[126:129]
	v_mfma_f32_16x16x32_bf16 v[122:125], v[152:155], v[176:179], v[122:125]
	v_mfma_f32_16x16x32_bf16 v[118:121], v[144:147], v[184:187], v[118:121]
	v_mfma_f32_16x16x32_bf16 v[114:117], v[152:155], v[184:187], v[114:117]
	v_mfma_f32_16x16x32_bf16 v[110:113], v[144:147], v[192:195], v[110:113]
	v_mfma_f32_16x16x32_bf16 v[106:109], v[152:155], v[192:195], v[106:109]
	v_mfma_f32_16x16x32_bf16 v[102:105], v[144:147], v[200:203], v[102:105]
	v_mfma_f32_16x16x32_bf16 v[98:101], v[152:155], v[200:203], v[98:101]
	v_mfma_f32_16x16x32_bf16 v[126:129], v[148:151], v[180:183], v[126:129]
	v_mfma_f32_16x16x32_bf16 v[122:125], v[156:159], v[180:183], v[122:125]
	v_mfma_f32_16x16x32_bf16 v[118:121], v[148:151], v[188:191], v[118:121]
	v_mfma_f32_16x16x32_bf16 v[114:117], v[156:159], v[188:191], v[114:117]
	v_mfma_f32_16x16x32_bf16 v[110:113], v[148:151], v[196:199], v[110:113]
	v_mfma_f32_16x16x32_bf16 v[106:109], v[156:159], v[196:199], v[106:109]
	v_mfma_f32_16x16x32_bf16 v[102:105], v[148:151], v[208:211], v[102:105]
	v_mfma_f32_16x16x32_bf16 v[98:101], v[156:159], v[208:211], v[98:101]
	v_mfma_f32_16x16x32_bf16 v[62:65], v[160:163], v[176:179], v[62:65]
	v_mfma_f32_16x16x32_bf16 v[58:61], v[168:171], v[176:179], v[58:61]
	v_mfma_f32_16x16x32_bf16 v[54:57], v[160:163], v[184:187], v[54:57]
	v_mfma_f32_16x16x32_bf16 v[50:53], v[168:171], v[184:187], v[50:53]
	v_mfma_f32_16x16x32_bf16 v[46:49], v[160:163], v[192:195], v[46:49]
	v_mfma_f32_16x16x32_bf16 v[42:45], v[168:171], v[192:195], v[42:45]
	v_mfma_f32_16x16x32_bf16 v[38:41], v[160:163], v[200:203], v[38:41]
	v_mfma_f32_16x16x32_bf16 v[34:37], v[168:171], v[200:203], v[34:37]
	v_mfma_f32_16x16x32_bf16 v[62:65], v[164:167], v[180:183], v[62:65]
	v_mfma_f32_16x16x32_bf16 v[58:61], v[172:175], v[180:183], v[58:61]
	v_mfma_f32_16x16x32_bf16 v[54:57], v[164:167], v[188:191], v[54:57]
	v_mfma_f32_16x16x32_bf16 v[50:53], v[172:175], v[188:191], v[50:53]
	v_mfma_f32_16x16x32_bf16 v[46:49], v[164:167], v[196:199], v[46:49]
	v_mfma_f32_16x16x32_bf16 v[42:45], v[172:175], v[196:199], v[42:45]
	v_mfma_f32_16x16x32_bf16 v[38:41], v[164:167], v[208:211], v[38:41]
	v_mfma_f32_16x16x32_bf16 v[34:37], v[172:175], v[208:211], v[34:37]
	s_barrier
	s_setprio 0
	s_mov_b32 m0, s33
	v_lshl_add_u64 v[140:141], s[22:23], 0, v[0:1]
	s_add_u32 s20, s22, 0x20000
	s_addc_u32 s21, s23, 0
	ds_read_b128 v[176:179], v143 offset:16384
	ds_read_b128 v[180:183], v143 offset:17408
	ds_read_b128 v[184:187], v143 offset:18432
	ds_read_b128 v[188:191], v143 offset:19456
	ds_read_b128 v[192:195], v143 offset:20480
	ds_read_b128 v[196:199], v143 offset:21504
	ds_read_b128 v[200:203], v143 offset:22528
	ds_read_b128 v[208:211], v143 offset:23552
	s_cmp_lg_u32 s100, 0
	s_cbranch_scc1 .Ltl_kv_0s
	global_load_lds_dwordx4 v0, s[22:23]
	v_lshl_add_u64 v[204:205], s[22:23], 0, v[134:135]
	s_mov_b32 m0, s34
	s_nop 0
	global_load_lds_dwordx4 v134, s[22:23]
	s_mov_b32 m0, s43
	v_lshl_add_u64 v[212:213], s[24:25], 0, v[132:133]
	global_load_lds_dwordx4 v0, s[20:21]
	s_mov_b32 m0, s44
	s_nop 0
	global_load_lds_dwordx4 v134, s[20:21]
	v_lshl_add_u64 v[206:207], s[24:25], 0, v[130:131]
	s_mov_b32 m0, s45
	s_nop 0
	global_load_lds_dwordx4 v130, s[24:25]
	s_mov_b32 m0, s47
	s_nop 0
	global_load_lds_dwordx4 v132, s[24:25]
	s_waitcnt vmcnt(8)
	s_branch .Ltl_kv_0d

; #define PG8_STAGE(bufoff, gbase, voff) do { _Pragma("unroll") for (int _i = 0; _i < 2; ++_i) \
;         __builtin_amdgcn_global_load_lds((const unsigned*)((const char*)(gbase) + (voff)[_i]), (LAS unsigned*)(lds + (bufoff) + ldsw + _i * 8192), 16, 0, 0); } while (0)
; #define PG8_LDA(dst, b, h) do { _Pragma("unroll") for (int m = 0; m < NM; ++m) _Pragma("unroll") for (int k = 0; k < 2; ++k) dst[m][k] = *(const LAS bf16x8*)(lds + PG8_SA(b, h) + aoff + m * 2048 + k * 1024); } while (0)
; #define PG8_LDB(dst, b, h) do { _Pragma("unroll") for (int n = 0; n < 2; ++n) _Pragma("unroll") for (int k = 0; k < 2; ++k) dst[n][k] = *(const LAS bf16x8*)(lds + PG8_SB(b, h) + boff + n * 2048 + k * 1024); } while (0)
; #define PG8_MMA(ai, bj, At, Bt) do { __builtin_amdgcn_s_setprio(1); _Pragma("unroll") for (int m = 0; m < NM; ++m) _Pragma("unroll") for (int n = 0; n < 2; ++n) _Pragma("unroll") for (int k = 0; k < 2; ++k) \
;         acc[ai][bj][m][n] = __builtin_amdgcn_mfma_f32_16x16x32_bf16(Bt[n][k], At[m][k], acc[ai][bj][m][n], 0, 0, 0); __builtin_amdgcn_s_setprio(0); } while (0)
; #define PG8_WAIT_V(n) asm volatile("s_waitcnt vmcnt(" #n ")" ::: "memory")
; #define PG8_WAIT_L(n) asm volatile("s_waitcnt lgkmcnt(" #n ")" ::: "memory")
; #define PG8_BAR __builtin_amdgcn_s_barrier()
; #define PG8_SCHED __builtin_amdgcn_sched_barrier(0)
;     ...
;             PG8_WAIT_V(8); PG8_WAIT_L(0); PG8_BAR; PG8_MMA(1, 0, At, B0); PG8_MMA(1, 1, At, B1); PG8_BAR; PG8_SCHED;
;             PG8_LDB(B0, 1, 0); PG8_LDB(B1, 1, 1); PG8_SCHED; PG8_LDA(At, 1, 0); PG8_STAGE(PG8_SA(0, 1), a2 + hstepA, voffA);
.Ltl_kv_0d:
	s_waitcnt lgkmcnt(0)
	s_setprio 1
	s_barrier
	v_mfma_f32_16x16x32_bf16 v[94:97], v[144:147], v[176:179], v[94:97]
	v_mfma_f32_16x16x32_bf16 v[90:93], v[152:155], v[176:179], v[90:93]
	v_mfma_f32_16x16x32_bf16 v[86:89], v[144:147], v[184:187], v[86:89]
	v_mfma_f32_16x16x32_bf16 v[82:85], v[152:155], v[184:187], v[82:85]
	v_mfma_f32_16x16x32_bf16 v[78:81], v[144:147], v[192:195], v[78:81]
	v_mfma_f32_16x16x32_bf16 v[74:77], v[152:155], v[192:195], v[74:77]
	v_mfma_f32_16x16x32_bf16 v[70:73], v[144:147], v[200:203], v[70:73]
	v_mfma_f32_16x16x32_bf16 v[66:69], v[152:155], v[200:203], v[66:69]
	v_mfma_f32_16x16x32_bf16 v[94:97], v[148:151], v[180:183], v[94:97]
	v_mfma_f32_16x16x32_bf16 v[90:93], v[156:159], v[180:183], v[90:93]
	v_mfma_f32_16x16x32_bf16 v[86:89], v[148:151], v[188:191], v[86:89]
	v_mfma_f32_16x16x32_bf16 v[82:85], v[156:159], v[188:191], v[82:85]
	v_mfma_f32_16x16x32_bf16 v[78:81], v[148:151], v[196:199], v[78:81]
	v_mfma_f32_16x16x32_bf16 v[74:77], v[156:159], v[196:199], v[74:77]
	v_mfma_f32_16x16x32_bf16 v[70:73], v[148:151], v[208:211], v[70:73]
	v_mfma_f32_16x16x32_bf16 v[66:69], v[156:159], v[208:211], v[66:69]
	v_mfma_f32_16x16x32_bf16 v[30:33], v[160:163], v[176:179], v[30:33]
	v_mfma_f32_16x16x32_bf16 v[26:29], v[168:171], v[176:179], v[26:29]
	v_mfma_f32_16x16x32_bf16 v[22:25], v[160:163], v[184:187], v[22:25]
	v_mfma_f32_16x16x32_bf16 v[18:21], v[168:171], v[184:187], v[18:21]
	v_mfma_f32_16x16x32_bf16 v[14:17], v[160:163], v[192:195], v[14:17]
	v_mfma_f32_16x16x32_bf16 v[10:13], v[168:171], v[192:195], v[10:13]
	v_mfma_f32_16x16x32_bf16 v[6:9], v[160:163], v[200:203], v[6:9]
	v_mfma_f32_16x16x32_bf16 v[2:5], v[168:171], v[200:203], v[2:5]
	v_mfma_f32_16x16x32_bf16 v[30:33], v[164:167], v[180:183], v[30:33]
	v_mfma_f32_16x16x32_bf16 v[26:29], v[172:175], v[180:183], v[26:29]
	v_mfma_f32_16x16x32_bf16 v[22:25], v[164:167], v[188:191], v[22:25]
	v_mfma_f32_16x16x32_bf16 v[18:21], v[172:175], v[188:191], v[18:21]
	v_mfma_f32_16x16x32_bf16 v[14:17], v[164:167], v[196:199], v[14:17]
	v_mfma_f32_16x16x32_bf16 v[10:13], v[172:175], v[196:199], v[10:13]
	v_mfma_f32_16x16x32_bf16 v[6:9], v[164:167], v[208:211], v[6:9]
	v_mfma_f32_16x16x32_bf16 v[2:5], v[172:175], v[208:211], v[2:5]
	s_barrier
	s_setprio 0
	v_add_u32_e32 v156, s50, v142
	v_add_u32_e32 v172, s57, v142
	ds_read_b128 v[144:147], v156
	ds_read_b128 v[148:151], v156 offset:1024
	ds_read_b128 v[152:155], v156 offset:2048
	ds_read_b128 v[156:159], v156 offset:3072
	ds_read_b128 v[160:163], v172
	ds_read_b128 v[164:167], v172 offset:1024
	ds_read_b128 v[168:171], v172 offset:2048
	ds_read_b128 v[172:175], v172 offset:3072
	s_add_u32 s20, s24, 0x24000
	s_addc_u32 s21, s25, 0
	s_mov_b32 m0, s48
	ds_read_b128 v[176:179], v143 offset:32768
	ds_read_b128 v[180:183], v143 offset:33792
	ds_read_b128 v[184:187], v143 offset:34816
	ds_read_b128 v[188:191], v143 offset:35840
	ds_read_b128 v[192:195], v143 offset:36864
	ds_read_b128 v[196:199], v143 offset:37888
	ds_read_b128 v[200:203], v143 offset:38912
	ds_read_b128 v[208:211], v143 offset:39936
	s_cmp_lg_u32 s100, 0
	s_cbranch_scc1 .Ltl_kv_1s
	global_load_lds_dwordx4 v130, s[20:21]
	s_mov_b32 m0, s49
	s_nop 0
	global_load_lds_dwordx4 v132, s[20:21]
	s_waitcnt vmcnt(8)
	s_branch .Ltl_kv_1d

; #define PG8_STAGE(bufoff, gbase, voff) do { _Pragma("unroll") for (int _i = 0; _i < 2; ++_i) \
;         __builtin_amdgcn_global_load_lds((const unsigned*)((const char*)(gbase) + (voff)[_i]), (LAS unsigned*)(lds + (bufoff) + ldsw + _i * 8192), 16, 0, 0); } while (0)
; #define PG8_LDA(dst, b, h) do { _Pragma("unroll") for (int m = 0; m < NM; ++m) _Pragma("unroll") for (int k = 0; k < 2; ++k) dst[m][k] = *(const LAS bf16x8*)(lds + PG8_SA(b, h) + aoff + m * 2048 + k * 1024); } while (0)
; #define PG8_MMA(ai, bj, At, Bt) do { __builtin_amdgcn_s_setprio(1); _Pragma("unroll") for (int m = 0; m < NM; ++m) _Pragma("unroll") for (int n = 0; n < 2; ++n) _Pragma("unroll") for (int k = 0; k < 2; ++k) \
;         acc[ai][bj][m][n] = __builtin_amdgcn_mfma_f32_16x16x32_bf16(Bt[n][k], At[m][k], acc[ai][bj][m][n], 0, 0, 0); __builtin_amdgcn_s_setprio(0); } while (0)
; #define PG8_WAIT_V(n) asm volatile("s_waitcnt vmcnt(" #n ")" ::: "memory")
; #define PG8_WAIT_L(n) asm volatile("s_waitcnt lgkmcnt(" #n ")" ::: "memory")
; #define PG8_BAR __builtin_amdgcn_s_barrier()
; #define PG8_SCHED __builtin_amdgcn_sched_barrier(0)
;     ...
;             PG8_WAIT_V(8); PG8_WAIT_L(0); PG8_BAR; PG8_MMA(0, 0, At, B0); PG8_MMA(0, 1, At, B1); PG8_BAR; PG8_SCHED;
;             PG8_LDA(At, 1, 1); PG8_STAGE(PG8_SB(1, 0), b3, voffB); PG8_STAGE(PG8_SB(1, 1), b3 + hstepB, voffB); PG8_STAGE(PG8_SA(1, 0), a3, voffA);
.Ltl_kv_1d:
	s_waitcnt lgkmcnt(0)
	s_setprio 1
	s_barrier
	v_mfma_f32_16x16x32_bf16 v[126:129], v[144:147], v[176:179], v[126:129]
	v_mfma_f32_16x16x32_bf16 v[122:125], v[152:155], v[176:179], v[122:125]
	v_mfma_f32_16x16x32_bf16 v[118:121], v[144:147], v[184:187], v[118:121]
	v_mfma_f32_16x16x32_bf16 v[114:117], v[152:155], v[184:187], v[114:117]
	v_mfma_f32_16x16x32_bf16 v[110:113], v[144:147], v[192:195], v[110:113]
	v_mfma_f32_16x16x32_bf16 v[106:109], v[152:155], v[192:195], v[106:109]
	v_mfma_f32_16x16x32_bf16 v[102:105], v[144:147], v[200:203], v[102:105]
	v_mfma_f32_16x16x32_bf16 v[98:101], v[152:155], v[200:203], v[98:101]
	v_mfma_f32_16x16x32_bf16 v[126:129], v[148:151], v[180:183], v[126:129]
	v_mfma_f32_16x16x32_bf16 v[122:125], v[156:159], v[180:183], v[122:125]
	v_mfma_f32_16x16x32_bf16 v[118:121], v[148:151], v[188:191], v[118:121]
	v_mfma_f32_16x16x32_bf16 v[114:117], v[156:159], v[188:191], v[114:117]
	v_mfma_f32_16x16x32_bf16 v[110:113], v[148:151], v[196:199], v[110:113]
	v_mfma_f32_16x16x32_bf16 v[106:109], v[156:159], v[196:199], v[106:109]
	v_mfma_f32_16x16x32_bf16 v[102:105], v[148:151], v[208:211], v[102:105]
	v_mfma_f32_16x16x32_bf16 v[98:101], v[156:159], v[208:211], v[98:101]
	v_mfma_f32_16x16x32_bf16 v[62:65], v[160:163], v[176:179], v[62:65]
	v_mfma_f32_16x16x32_bf16 v[58:61], v[168:171], v[176:179], v[58:61]
	v_mfma_f32_16x16x32_bf16 v[54:57], v[160:163], v[184:187], v[54:57]
	v_mfma_f32_16x16x32_bf16 v[50:53], v[168:171], v[184:187], v[50:53]
	v_mfma_f32_16x16x32_bf16 v[46:49], v[160:163], v[192:195], v[46:49]
	v_mfma_f32_16x16x32_bf16 v[42:45], v[168:171], v[192:195], v[42:45]
	v_mfma_f32_16x16x32_bf16 v[38:41], v[160:163], v[200:203], v[38:41]
	v_mfma_f32_16x16x32_bf16 v[34:37], v[168:171], v[200:203], v[34:37]
	v_mfma_f32_16x16x32_bf16 v[62:65], v[164:167], v[180:183], v[62:65]
	v_mfma_f32_16x16x32_bf16 v[58:61], v[172:175], v[180:183], v[58:61]
	v_mfma_f32_16x16x32_bf16 v[54:57], v[164:167], v[188:191], v[54:57]
	v_mfma_f32_16x16x32_bf16 v[50:53], v[172:175], v[188:191], v[50:53]
	v_mfma_f32_16x16x32_bf16 v[46:49], v[164:167], v[196:199], v[46:49]
	v_mfma_f32_16x16x32_bf16 v[42:45], v[172:175], v[196:199], v[42:45]
	v_mfma_f32_16x16x32_bf16 v[38:41], v[164:167], v[208:211], v[38:41]
	v_mfma_f32_16x16x32_bf16 v[34:37], v[172:175], v[208:211], v[34:37]
	s_barrier
	s_setprio 0
	s_mov_b32 m0, s51
	v_lshl_add_u64 v[140:141], v[140:141], 0, s[66:67]
	s_add_u32 s20, s22, 0x20080
	s_addc_u32 s21, s23, 0
	ds_read_b128 v[176:179], v143 offset:49152
	ds_read_b128 v[180:183], v143 offset:50176
	ds_read_b128 v[184:187], v143 offset:51200
	ds_read_b128 v[188:191], v143 offset:52224
	ds_read_b128 v[192:195], v143 offset:53248
	ds_read_b128 v[196:199], v143 offset:54272
	ds_read_b128 v[200:203], v143 offset:55296
	ds_read_b128 v[208:211], v143 offset:56320
	s_cmp_lg_u32 s100, 0
	s_cbranch_scc1 .Ltl_kv_2s
	global_load_lds_dwordx4 v[140:141], off
	v_lshl_add_u64 v[140:141], v[204:205], 0, s[66:67]
	s_mov_b32 m0, s52
	s_nop 0
	global_load_lds_dwordx4 v[140:141], off
	s_mov_b32 m0, s58
	s_nop 0
	global_load_lds_dwordx4 v0, s[20:21]
	s_mov_b32 m0, s59
	s_nop 0
	global_load_lds_dwordx4 v134, s[20:21]
	v_lshl_add_u64 v[140:141], v[206:207], 0, s[66:67]
	s_mov_b32 m0, s54
	s_nop 0
	global_load_lds_dwordx4 v[140:141], off
	v_lshl_add_u64 v[140:141], v[212:213], 0, s[66:67]
	s_mov_b32 m0, s56
	s_nop 0
	global_load_lds_dwordx4 v[140:141], off
	s_waitcnt vmcnt(8)
	s_branch .Ltl_kv_2d

; #define PG8_MMA(ai, bj, At, Bt) do { __builtin_amdgcn_s_setprio(1); _Pragma("unroll") for (int m = 0; m < NM; ++m) _Pragma("unroll") for (int n = 0; n < 2; ++n) _Pragma("unroll") for (int k = 0; k < 2; ++k) \
;         acc[ai][bj][m][n] = __builtin_amdgcn_mfma_f32_16x16x32_bf16(Bt[n][k], At[m][k], acc[ai][bj][m][n], 0, 0, 0); __builtin_amdgcn_s_setprio(0); } while (0)
; #define PG8_WAIT_V(n) asm volatile("s_waitcnt vmcnt(" #n ")" ::: "memory")
; #define PG8_WAIT_L(n) asm volatile("s_waitcnt lgkmcnt(" #n ")" ::: "memory")
; #define PG8_BAR __builtin_amdgcn_s_barrier()
; #define PG8_SCHED __builtin_amdgcn_sched_barrier(0)
;     ...
;             PG8_WAIT_V(8); PG8_WAIT_L(0); PG8_BAR; PG8_MMA(1, 0, At, B0); PG8_MMA(1, 1, At, B1); PG8_BAR; PG8_SCHED;
;     ...
;         }
;         if constexpr (ALIGN_EPI) { if (wr == 0) PG8_BAR; }
.Ltl_kv_2d:
	s_waitcnt lgkmcnt(0)
	s_setprio 1
	s_barrier
	v_mfma_f32_16x16x32_bf16 v[94:97], v[144:147], v[176:179], v[94:97]
	v_mfma_f32_16x16x32_bf16 v[90:93], v[152:155], v[176:179], v[90:93]
	v_mfma_f32_16x16x32_bf16 v[86:89], v[144:147], v[184:187], v[86:89]
	v_mfma_f32_16x16x32_bf16 v[82:85], v[152:155], v[184:187], v[82:85]
	v_mfma_f32_16x16x32_bf16 v[78:81], v[144:147], v[192:195], v[78:81]
	v_mfma_f32_16x16x32_bf16 v[74:77], v[152:155], v[192:195], v[74:77]
	v_mfma_f32_16x16x32_bf16 v[70:73], v[144:147], v[200:203], v[70:73]
	v_mfma_f32_16x16x32_bf16 v[66:69], v[152:155], v[200:203], v[66:69]
	v_mfma_f32_16x16x32_bf16 v[94:97], v[148:151], v[180:183], v[94:97]
	v_mfma_f32_16x16x32_bf16 v[90:93], v[156:159], v[180:183], v[90:93]
	v_mfma_f32_16x16x32_bf16 v[86:89], v[148:151], v[188:191], v[86:89]
	v_mfma_f32_16x16x32_bf16 v[82:85], v[156:159], v[188:191], v[82:85]
	v_mfma_f32_16x16x32_bf16 v[78:81], v[148:151], v[196:199], v[78:81]
	v_mfma_f32_16x16x32_bf16 v[74:77], v[156:159], v[196:199], v[74:77]
	v_mfma_f32_16x16x32_bf16 v[70:73], v[148:151], v[208:211], v[70:73]
	v_mfma_f32_16x16x32_bf16 v[66:69], v[156:159], v[208:211], v[66:69]
	v_mfma_f32_16x16x32_bf16 v[30:33], v[160:163], v[176:179], v[30:33]
	v_mfma_f32_16x16x32_bf16 v[26:29], v[168:171], v[176:179], v[26:29]
	v_mfma_f32_16x16x32_bf16 v[22:25], v[160:163], v[184:187], v[22:25]
	v_mfma_f32_16x16x32_bf16 v[18:21], v[168:171], v[184:187], v[18:21]
	v_mfma_f32_16x16x32_bf16 v[14:17], v[160:163], v[192:195], v[14:17]
	v_mfma_f32_16x16x32_bf16 v[10:13], v[168:171], v[192:195], v[10:13]
	v_mfma_f32_16x16x32_bf16 v[6:9], v[160:163], v[200:203], v[6:9]
	v_mfma_f32_16x16x32_bf16 v[2:5], v[168:171], v[200:203], v[2:5]
	v_mfma_f32_16x16x32_bf16 v[30:33], v[164:167], v[180:183], v[30:33]
	v_mfma_f32_16x16x32_bf16 v[26:29], v[172:175], v[180:183], v[26:29]
	v_mfma_f32_16x16x32_bf16 v[22:25], v[164:167], v[188:191], v[22:25]
	v_mfma_f32_16x16x32_bf16 v[18:21], v[172:175], v[188:191], v[18:21]
	v_mfma_f32_16x16x32_bf16 v[14:17], v[164:167], v[196:199], v[14:17]
	v_mfma_f32_16x16x32_bf16 v[10:13], v[172:175], v[196:199], v[10:13]
	v_mfma_f32_16x16x32_bf16 v[6:9], v[164:167], v[208:211], v[6:9]
	v_mfma_f32_16x16x32_bf16 v[2:5], v[172:175], v[208:211], v[2:5]
	s_barrier
	s_setprio 0
	s_add_i32 s73, s73, 2
	s_add_u32 s15, s15, 0x100
	s_addc_u32 s60, s60, 0
	s_cmp_gt_u32 s73, 5
	s_mov_b64 s[20:21], s[6:7]
	s_cbranch_scc0 .LBB0_1454
	s_and_b64 vcc, exec, s[12:13]
	s_cbranch_vccz .LBB0_1457
	s_barrier

; #define PG8_STAGE(bufoff, gbase, voff) do { _Pragma("unroll") for (int _i = 0; _i < 2; ++_i) \
;         __builtin_amdgcn_global_load_lds((const unsigned*)((const char*)(gbase) + (voff)[_i]), (LAS unsigned*)(lds + (bufoff) + ldsw + _i * 8192), 16, 0, 0); } while (0)
; #define PG8_LDA(dst, b, h) do { _Pragma("unroll") for (int m = 0; m < NM; ++m) _Pragma("unroll") for (int k = 0; k < 2; ++k) dst[m][k] = *(const LAS bf16x8*)(lds + PG8_SA(b, h) + aoff + m * 2048 + k * 1024); } while (0)
; #define PG8_MMA(ai, bj, At, Bt) do { __builtin_amdgcn_s_setprio(1); _Pragma("unroll") for (int m = 0; m < NM; ++m) _Pragma("unroll") for (int n = 0; n < 2; ++n) _Pragma("unroll") for (int k = 0; k < 2; ++k) \
;         acc[ai][bj][m][n] = __builtin_amdgcn_mfma_f32_16x16x32_bf16(Bt[n][k], At[m][k], acc[ai][bj][m][n], 0, 0, 0); __builtin_amdgcn_s_setprio(0); } while (0)
; #define PG8_WAIT_V(n) asm volatile("s_waitcnt vmcnt(" #n ")" ::: "memory")
; #define PG8_WAIT_L(n) asm volatile("s_waitcnt lgkmcnt(" #n ")" ::: "memory")
; #define PG8_BAR __builtin_amdgcn_s_barrier()
; #define PG8_SCHED __builtin_amdgcn_sched_barrier(0)
;     ...
;             PG8_WAIT_V(8); PG8_WAIT_L(0); PG8_BAR; PG8_MMA(0, 0, At, B0); PG8_MMA(0, 1, At, B1); PG8_BAR; PG8_SCHED;
;             PG8_LDA(At, 0, 1); PG8_STAGE(PG8_SB(0, 0), b2, voffB); PG8_STAGE(PG8_SB(0, 1), b2 + hstepB, voffB); PG8_STAGE(PG8_SA(0, 0), a2, voffA);
.Lnm3o_done0:
	s_waitcnt lgkmcnt(0)
	s_setprio 1
	s_barrier
	v_mfma_f32_16x16x32_bf16 v[110:113], v[90:93], v[130:133], v[110:113]
	v_mfma_f32_16x16x32_bf16 v[106:109], v[98:101], v[130:133], v[106:109]
	v_mfma_f32_16x16x32_bf16 v[78:81], v[90:93], v[138:141], v[78:81]
	v_mfma_f32_16x16x32_bf16 v[74:77], v[98:101], v[138:141], v[74:77]
	v_mfma_f32_16x16x32_bf16 v[62:65], v[90:93], v[156:159], v[62:65]
	v_mfma_f32_16x16x32_bf16 v[58:61], v[98:101], v[156:159], v[58:61]
	v_mfma_f32_16x16x32_bf16 v[110:113], v[94:97], v[134:137], v[110:113]
	v_mfma_f32_16x16x32_bf16 v[106:109], v[102:105], v[134:137], v[106:109]
	v_mfma_f32_16x16x32_bf16 v[78:81], v[94:97], v[152:155], v[78:81]
	v_mfma_f32_16x16x32_bf16 v[74:77], v[102:105], v[152:155], v[74:77]
	v_mfma_f32_16x16x32_bf16 v[62:65], v[94:97], v[160:163], v[62:65]
	v_mfma_f32_16x16x32_bf16 v[58:61], v[102:105], v[160:163], v[58:61]
	v_mfma_f32_16x16x32_bf16 v[86:89], v[114:117], v[130:133], v[86:89]
	v_mfma_f32_16x16x32_bf16 v[82:85], v[122:125], v[130:133], v[82:85]
	v_mfma_f32_16x16x32_bf16 v[70:73], v[114:117], v[138:141], v[70:73]
	v_mfma_f32_16x16x32_bf16 v[66:69], v[122:125], v[138:141], v[66:69]
	v_mfma_f32_16x16x32_bf16 v[54:57], v[114:117], v[156:159], v[54:57]
	v_mfma_f32_16x16x32_bf16 v[50:53], v[122:125], v[156:159], v[50:53]
	v_mfma_f32_16x16x32_bf16 v[86:89], v[118:121], v[134:137], v[86:89]
	v_mfma_f32_16x16x32_bf16 v[82:85], v[126:129], v[134:137], v[82:85]
	v_mfma_f32_16x16x32_bf16 v[70:73], v[118:121], v[152:155], v[70:73]
	v_mfma_f32_16x16x32_bf16 v[66:69], v[126:129], v[152:155], v[66:69]
	v_mfma_f32_16x16x32_bf16 v[54:57], v[118:121], v[160:163], v[54:57]
	v_mfma_f32_16x16x32_bf16 v[50:53], v[126:129], v[160:163], v[50:53]
	s_barrier
	s_setprio 0
	s_mov_b32 m0, s29
	v_lshl_add_u64 v[164:165], s[22:23], 0, v[0:1]
	s_add_u32 s62, s22, 0x80000
	s_addc_u32 s63, s23, 0
	ds_read_b128 v[130:133], v167 offset:16384
	ds_read_b128 v[134:137], v167 offset:17408
	ds_read_b128 v[138:141], v167 offset:18432
	ds_read_b128 v[152:155], v167 offset:19456
	ds_read_b128 v[156:159], v167 offset:20480
	ds_read_b128 v[160:163], v167 offset:21504
	s_cmp_lg_u32 s100, 0
	s_cbranch_scc1 .Ltl_ou_0s
	global_load_lds_dwordx4 v0, s[22:23]
	v_lshl_add_u64 v[168:169], s[22:23], 0, v[146:147]
	s_mov_b32 m0, s30
	s_nop 0
	global_load_lds_dwordx4 v146, s[22:23]
	s_mov_b32 m0, s33
	v_lshl_add_u64 v[172:173], s[24:25], 0, v[144:145]
	global_load_lds_dwordx4 v0, s[62:63]
	s_mov_b32 m0, s34
	s_nop 0
	global_load_lds_dwordx4 v146, s[62:63]
	v_lshl_add_u64 v[170:171], s[24:25], 0, v[142:143]
	s_mov_b32 m0, s35
	s_nop 0
	global_load_lds_dwordx4 v142, s[24:25]
	s_mov_b32 m0, s36
	s_nop 0
	s_and_b64 vcc, exec, s[10:11]
	s_cbranch_vccz .Lnm3o_skip1
	global_load_lds_dwordx4 v144, s[24:25]
	s_waitcnt vmcnt(8)
	s_branch .Lnm3o_done1

; #define PG8_STAGE(bufoff, gbase, voff) do { _Pragma("unroll") for (int _i = 0; _i < 2; ++_i) \
;         __builtin_amdgcn_global_load_lds((const unsigned*)((const char*)(gbase) + (voff)[_i]), (LAS unsigned*)(lds + (bufoff) + ldsw + _i * 8192), 16, 0, 0); } while (0)
; #define PG8_LDA(dst, b, h) do { _Pragma("unroll") for (int m = 0; m < NM; ++m) _Pragma("unroll") for (int k = 0; k < 2; ++k) dst[m][k] = *(const LAS bf16x8*)(lds + PG8_SA(b, h) + aoff + m * 2048 + k * 1024); } while (0)
; #define PG8_LDB(dst, b, h) do { _Pragma("unroll") for (int n = 0; n < 2; ++n) _Pragma("unroll") for (int k = 0; k < 2; ++k) dst[n][k] = *(const LAS bf16x8*)(lds + PG8_SB(b, h) + boff + n * 2048 + k * 1024); } while (0)
; #define PG8_MMA(ai, bj, At, Bt) do { __builtin_amdgcn_s_setprio(1); _Pragma("unroll") for (int m = 0; m < NM; ++m) _Pragma("unroll") for (int n = 0; n < 2; ++n) _Pragma("unroll") for (int k = 0; k < 2; ++k) \
;         acc[ai][bj][m][n] = __builtin_amdgcn_mfma_f32_16x16x32_bf16(Bt[n][k], At[m][k], acc[ai][bj][m][n], 0, 0, 0); __builtin_amdgcn_s_setprio(0); } while (0)
; #define PG8_WAIT_V(n) asm volatile("s_waitcnt vmcnt(" #n ")" ::: "memory")
; #define PG8_WAIT_L(n) asm volatile("s_waitcnt lgkmcnt(" #n ")" ::: "memory")
; #define PG8_BAR __builtin_amdgcn_s_barrier()
; #define PG8_SCHED __builtin_amdgcn_sched_barrier(0)
;     ...
;             PG8_WAIT_V(8); PG8_WAIT_L(0); PG8_BAR; PG8_MMA(1, 0, At, B0); PG8_MMA(1, 1, At, B1); PG8_BAR; PG8_SCHED;
;             PG8_LDB(B0, 1, 0); PG8_LDB(B1, 1, 1); PG8_SCHED; PG8_LDA(At, 1, 0); PG8_STAGE(PG8_SA(0, 1), a2 + hstepA, voffA);
.Ltl_ou_0d:
	s_waitcnt lgkmcnt(0)
	s_setprio 1
	s_barrier
	v_mfma_f32_16x16x32_bf16 v[46:49], v[90:93], v[130:133], v[46:49]
	v_mfma_f32_16x16x32_bf16 v[42:45], v[98:101], v[130:133], v[42:45]
	v_mfma_f32_16x16x32_bf16 v[30:33], v[90:93], v[138:141], v[30:33]
	v_mfma_f32_16x16x32_bf16 v[26:29], v[98:101], v[138:141], v[26:29]
	v_mfma_f32_16x16x32_bf16 v[14:17], v[90:93], v[156:159], v[14:17]
	v_mfma_f32_16x16x32_bf16 v[10:13], v[98:101], v[156:159], v[10:13]
	v_mfma_f32_16x16x32_bf16 v[46:49], v[94:97], v[134:137], v[46:49]
	v_mfma_f32_16x16x32_bf16 v[42:45], v[102:105], v[134:137], v[42:45]
	v_mfma_f32_16x16x32_bf16 v[30:33], v[94:97], v[152:155], v[30:33]
	v_mfma_f32_16x16x32_bf16 v[26:29], v[102:105], v[152:155], v[26:29]
	v_mfma_f32_16x16x32_bf16 v[14:17], v[94:97], v[160:163], v[14:17]
	v_mfma_f32_16x16x32_bf16 v[10:13], v[102:105], v[160:163], v[10:13]
	v_mfma_f32_16x16x32_bf16 v[38:41], v[114:117], v[130:133], v[38:41]
	v_mfma_f32_16x16x32_bf16 v[34:37], v[122:125], v[130:133], v[34:37]
	v_mfma_f32_16x16x32_bf16 v[22:25], v[114:117], v[138:141], v[22:25]
	v_mfma_f32_16x16x32_bf16 v[18:21], v[122:125], v[138:141], v[18:21]
	v_mfma_f32_16x16x32_bf16 v[6:9], v[114:117], v[156:159], v[6:9]
	v_mfma_f32_16x16x32_bf16 v[2:5], v[122:125], v[156:159], v[2:5]
	v_mfma_f32_16x16x32_bf16 v[38:41], v[118:121], v[134:137], v[38:41]
	v_mfma_f32_16x16x32_bf16 v[34:37], v[126:129], v[134:137], v[34:37]
	v_mfma_f32_16x16x32_bf16 v[22:25], v[118:121], v[152:155], v[22:25]
	v_mfma_f32_16x16x32_bf16 v[18:21], v[126:129], v[152:155], v[18:21]
	v_mfma_f32_16x16x32_bf16 v[6:9], v[118:121], v[160:163], v[6:9]
	v_mfma_f32_16x16x32_bf16 v[2:5], v[126:129], v[160:163], v[2:5]
	s_barrier
	s_setprio 0
	v_add_u32_e32 v102, s40, v166
	v_add_u32_e32 v126, s45, v166
	ds_read_b128 v[90:93], v102
	ds_read_b128 v[94:97], v102 offset:1024
	ds_read_b128 v[98:101], v102 offset:2048
	ds_read_b128 v[102:105], v102 offset:3072
	ds_read_b128 v[114:117], v126
	ds_read_b128 v[118:121], v126 offset:1024
	ds_read_b128 v[122:125], v126 offset:2048
	ds_read_b128 v[126:129], v126 offset:3072
	s_add_u32 s24, s24, 0x60000
	s_addc_u32 s25, s25, 0
	s_mov_b32 m0, s37
	ds_read_b128 v[130:133], v167 offset:32768
	ds_read_b128 v[134:137], v167 offset:33792
	ds_read_b128 v[138:141], v167 offset:34816
	ds_read_b128 v[152:155], v167 offset:35840
	ds_read_b128 v[156:159], v167 offset:36864
	ds_read_b128 v[160:163], v167 offset:37888
	s_cmp_lg_u32 s100, 0
	s_cbranch_scc1 .Ltl_ou_1s
	global_load_lds_dwordx4 v142, s[24:25]
	s_mov_b32 m0, s38
	s_nop 0
	s_and_b64 vcc, exec, s[10:11]
	s_cbranch_vccz .Lnm3o_skip2
	global_load_lds_dwordx4 v144, s[24:25]
	s_waitcnt vmcnt(8)
	s_branch .Lnm3o_done2

; #define PG8_STAGE(bufoff, gbase, voff) do { _Pragma("unroll") for (int _i = 0; _i < 2; ++_i) \
;         __builtin_amdgcn_global_load_lds((const unsigned*)((const char*)(gbase) + (voff)[_i]), (LAS unsigned*)(lds + (bufoff) + ldsw + _i * 8192), 16, 0, 0); } while (0)
; #define PG8_LDA(dst, b, h) do { _Pragma("unroll") for (int m = 0; m < NM; ++m) _Pragma("unroll") for (int k = 0; k < 2; ++k) dst[m][k] = *(const LAS bf16x8*)(lds + PG8_SA(b, h) + aoff + m * 2048 + k * 1024); } while (0)
; #define PG8_MMA(ai, bj, At, Bt) do { __builtin_amdgcn_s_setprio(1); _Pragma("unroll") for (int m = 0; m < NM; ++m) _Pragma("unroll") for (int n = 0; n < 2; ++n) _Pragma("unroll") for (int k = 0; k < 2; ++k) \
;         acc[ai][bj][m][n] = __builtin_amdgcn_mfma_f32_16x16x32_bf16(Bt[n][k], At[m][k], acc[ai][bj][m][n], 0, 0, 0); __builtin_amdgcn_s_setprio(0); } while (0)
; #define PG8_WAIT_V(n) asm volatile("s_waitcnt vmcnt(" #n ")" ::: "memory")
; #define PG8_WAIT_L(n) asm volatile("s_waitcnt lgkmcnt(" #n ")" ::: "memory")
; #define PG8_BAR __builtin_amdgcn_s_barrier()
; #define PG8_SCHED __builtin_amdgcn_sched_barrier(0)
;     ...
;             PG8_WAIT_V(8); PG8_WAIT_L(0); PG8_BAR; PG8_MMA(0, 0, At, B0); PG8_MMA(0, 1, At, B1); PG8_BAR; PG8_SCHED;
;             PG8_LDA(At, 1, 1); PG8_STAGE(PG8_SB(1, 0), b3, voffB); PG8_STAGE(PG8_SB(1, 1), b3 + hstepB, voffB); PG8_STAGE(PG8_SA(1, 0), a3, voffA);
.Ltl_ou_1d:
	s_waitcnt lgkmcnt(0)
	s_setprio 1
	s_barrier
	v_mfma_f32_16x16x32_bf16 v[110:113], v[90:93], v[130:133], v[110:113]
	v_mfma_f32_16x16x32_bf16 v[106:109], v[98:101], v[130:133], v[106:109]
	v_mfma_f32_16x16x32_bf16 v[78:81], v[90:93], v[138:141], v[78:81]
	v_mfma_f32_16x16x32_bf16 v[74:77], v[98:101], v[138:141], v[74:77]
	v_mfma_f32_16x16x32_bf16 v[62:65], v[90:93], v[156:159], v[62:65]
	v_mfma_f32_16x16x32_bf16 v[58:61], v[98:101], v[156:159], v[58:61]
	v_mfma_f32_16x16x32_bf16 v[110:113], v[94:97], v[134:137], v[110:113]
	v_mfma_f32_16x16x32_bf16 v[106:109], v[102:105], v[134:137], v[106:109]
	v_mfma_f32_16x16x32_bf16 v[78:81], v[94:97], v[152:155], v[78:81]
	v_mfma_f32_16x16x32_bf16 v[74:77], v[102:105], v[152:155], v[74:77]
	v_mfma_f32_16x16x32_bf16 v[62:65], v[94:97], v[160:163], v[62:65]
	v_mfma_f32_16x16x32_bf16 v[58:61], v[102:105], v[160:163], v[58:61]
	v_mfma_f32_16x16x32_bf16 v[86:89], v[114:117], v[130:133], v[86:89]
	v_mfma_f32_16x16x32_bf16 v[82:85], v[122:125], v[130:133], v[82:85]
	v_mfma_f32_16x16x32_bf16 v[70:73], v[114:117], v[138:141], v[70:73]
	v_mfma_f32_16x16x32_bf16 v[66:69], v[122:125], v[138:141], v[66:69]
	v_mfma_f32_16x16x32_bf16 v[54:57], v[114:117], v[156:159], v[54:57]
	v_mfma_f32_16x16x32_bf16 v[50:53], v[122:125], v[156:159], v[50:53]
	v_mfma_f32_16x16x32_bf16 v[86:89], v[118:121], v[134:137], v[86:89]
	v_mfma_f32_16x16x32_bf16 v[82:85], v[126:129], v[134:137], v[82:85]
	v_mfma_f32_16x16x32_bf16 v[70:73], v[118:121], v[152:155], v[70:73]
	v_mfma_f32_16x16x32_bf16 v[66:69], v[126:129], v[152:155], v[66:69]
	v_mfma_f32_16x16x32_bf16 v[54:57], v[118:121], v[160:163], v[54:57]
	v_mfma_f32_16x16x32_bf16 v[50:53], v[126:129], v[160:163], v[50:53]
	s_barrier
	s_setprio 0
	s_mov_b32 m0, s41
	v_lshl_add_u64 v[164:165], v[164:165], 0, s[66:67]
	s_add_u32 s22, s22, 0x80080
	s_addc_u32 s23, s23, 0
	ds_read_b128 v[130:133], v167 offset:49152
	ds_read_b128 v[134:137], v167 offset:50176
	ds_read_b128 v[138:141], v167 offset:51200
	ds_read_b128 v[152:155], v167 offset:52224
	ds_read_b128 v[156:159], v167 offset:53248
	ds_read_b128 v[160:163], v167 offset:54272
	s_cmp_lg_u32 s100, 0
	s_cbranch_scc1 .Ltl_ou_2s
	global_load_lds_dwordx4 v[164:165], off
	v_lshl_add_u64 v[164:165], v[168:169], 0, s[66:67]
	s_mov_b32 m0, s42
	s_nop 0
	global_load_lds_dwordx4 v[164:165], off
	s_mov_b32 m0, s46
	s_nop 0
	global_load_lds_dwordx4 v0, s[22:23]
	s_mov_b32 m0, s47
	s_nop 0
	global_load_lds_dwordx4 v146, s[22:23]
	v_lshl_add_u64 v[164:165], v[170:171], 0, s[66:67]
	s_mov_b32 m0, s43
	s_nop 0
	global_load_lds_dwordx4 v[164:165], off
	v_lshl_add_u64 v[164:165], v[172:173], 0, s[66:67]
	s_mov_b32 m0, s44
	s_nop 0
	s_and_b64 vcc, exec, s[10:11]
	s_cbranch_vccz .Lnm3o_skip3
	global_load_lds_dwordx4 v[164:165], off
	s_waitcnt vmcnt(8)
	s_branch .Lnm3o_done3

; #define PG8_MMA(ai, bj, At, Bt) do { __builtin_amdgcn_s_setprio(1); _Pragma("unroll") for (int m = 0; m < NM; ++m) _Pragma("unroll") for (int n = 0; n < 2; ++n) _Pragma("unroll") for (int k = 0; k < 2; ++k) \
;         acc[ai][bj][m][n] = __builtin_amdgcn_mfma_f32_16x16x32_bf16(Bt[n][k], At[m][k], acc[ai][bj][m][n], 0, 0, 0); __builtin_amdgcn_s_setprio(0); } while (0)
; #define PG8_WAIT_V(n) asm volatile("s_waitcnt vmcnt(" #n ")" ::: "memory")
; #define PG8_WAIT_L(n) asm volatile("s_waitcnt lgkmcnt(" #n ")" ::: "memory")
; #define PG8_BAR __builtin_amdgcn_s_barrier()
; #define PG8_SCHED __builtin_amdgcn_sched_barrier(0)
;     ...
;             PG8_WAIT_V(8); PG8_WAIT_L(0); PG8_BAR; PG8_MMA(1, 0, At, B0); PG8_MMA(1, 1, At, B1); PG8_BAR; PG8_SCHED;
;     ...
;         }
;         if constexpr (ALIGN_EPI) { if (wr == 0) PG8_BAR; }
.Ltl_ou_2d:
	s_waitcnt lgkmcnt(0)
	s_setprio 1
	s_barrier
	v_mfma_f32_16x16x32_bf16 v[46:49], v[90:93], v[130:133], v[46:49]
	v_mfma_f32_16x16x32_bf16 v[42:45], v[98:101], v[130:133], v[42:45]
	v_mfma_f32_16x16x32_bf16 v[30:33], v[90:93], v[138:141], v[30:33]
	v_mfma_f32_16x16x32_bf16 v[26:29], v[98:101], v[138:141], v[26:29]
	v_mfma_f32_16x16x32_bf16 v[14:17], v[90:93], v[156:159], v[14:17]
	v_mfma_f32_16x16x32_bf16 v[10:13], v[98:101], v[156:159], v[10:13]
	v_mfma_f32_16x16x32_bf16 v[46:49], v[94:97], v[134:137], v[46:49]
	v_mfma_f32_16x16x32_bf16 v[42:45], v[102:105], v[134:137], v[42:45]
	v_mfma_f32_16x16x32_bf16 v[30:33], v[94:97], v[152:155], v[30:33]
	v_mfma_f32_16x16x32_bf16 v[26:29], v[102:105], v[152:155], v[26:29]
	v_mfma_f32_16x16x32_bf16 v[14:17], v[94:97], v[160:163], v[14:17]
	v_mfma_f32_16x16x32_bf16 v[10:13], v[102:105], v[160:163], v[10:13]
	v_mfma_f32_16x16x32_bf16 v[38:41], v[114:117], v[130:133], v[38:41]
	v_mfma_f32_16x16x32_bf16 v[34:37], v[122:125], v[130:133], v[34:37]
	v_mfma_f32_16x16x32_bf16 v[22:25], v[114:117], v[138:141], v[22:25]
	v_mfma_f32_16x16x32_bf16 v[18:21], v[122:125], v[138:141], v[18:21]
	v_mfma_f32_16x16x32_bf16 v[6:9], v[114:117], v[156:159], v[6:9]
	v_mfma_f32_16x16x32_bf16 v[2:5], v[122:125], v[156:159], v[2:5]
	v_mfma_f32_16x16x32_bf16 v[38:41], v[118:121], v[134:137], v[38:41]
	v_mfma_f32_16x16x32_bf16 v[34:37], v[126:129], v[134:137], v[34:37]
	v_mfma_f32_16x16x32_bf16 v[22:25], v[118:121], v[152:155], v[22:25]
	v_mfma_f32_16x16x32_bf16 v[18:21], v[126:129], v[152:155], v[18:21]
	v_mfma_f32_16x16x32_bf16 v[6:9], v[118:121], v[160:163], v[6:9]
	v_mfma_f32_16x16x32_bf16 v[2:5], v[126:129], v[160:163], v[2:5]
	s_barrier
	s_setprio 0
	s_add_i32 s59, s59, 2
	s_add_u32 s8, s8, 0x100
	s_addc_u32 s9, s9, 0
	s_add_u32 s15, s15, 0x100
	s_addc_u32 s58, s58, 0
	s_cmp_gt_u32 s59, 29
	s_cbranch_scc0 .LBB0_1650
	s_and_b64 vcc, exec, s[10:11]
	s_cbranch_vccz .LBB0_1653
	s_barrier

; #define PG8_STAGE(bufoff, gbase, voff) do { _Pragma("unroll") for (int _i = 0; _i < 2; ++_i) \
;         __builtin_amdgcn_global_load_lds((const unsigned*)((const char*)(gbase) + (voff)[_i]), (LAS unsigned*)(lds + (bufoff) + ldsw + _i * 8192), 16, 0, 0); } while (0)
; #define PG8_LDA(dst, b, h) do { _Pragma("unroll") for (int m = 0; m < NM; ++m) _Pragma("unroll") for (int k = 0; k < 2; ++k) dst[m][k] = *(const LAS bf16x8*)(lds + PG8_SA(b, h) + aoff + m * 2048 + k * 1024); } while (0)
; #define PG8_LDB(dst, b, h) do { _Pragma("unroll") for (int n = 0; n < 2; ++n) _Pragma("unroll") for (int k = 0; k < 2; ++k) dst[n][k] = *(const LAS bf16x8*)(lds + PG8_SB(b, h) + boff + n * 2048 + k * 1024); } while (0)
; #define PG8_MMA(ai, bj, At, Bt) do { __builtin_amdgcn_s_setprio(1); _Pragma("unroll") for (int m = 0; m < NM; ++m) _Pragma("unroll") for (int n = 0; n < 2; ++n) _Pragma("unroll") for (int k = 0; k < 2; ++k) \
;         acc[ai][bj][m][n] = __builtin_amdgcn_mfma_f32_16x16x32_bf16(Bt[n][k], At[m][k], acc[ai][bj][m][n], 0, 0, 0); __builtin_amdgcn_s_setprio(0); } while (0)
; #define PG8_WAIT_V(n) asm volatile("s_waitcnt vmcnt(" #n ")" ::: "memory")
; #define PG8_WAIT_L(n) asm volatile("s_waitcnt lgkmcnt(" #n ")" ::: "memory")
; #define PG8_BAR __builtin_amdgcn_s_barrier()
; #define PG8_SCHED __builtin_amdgcn_sched_barrier(0)
;     ...
;         for (int t = 0; t < nt; t += 2) {
;             const bool last = (t == nt - 2);
;             const char* a1 = cA + (size_t)(t + 1) * kstep;
;             const char* a2 = last ? nA : cA + (size_t)(t + 2) * kstep; const char* b2 = last ? nB : cB + (size_t)(t + 2) * kstep;
;             const char* a3 = a2 + kstep; const char* b3 = b2 + kstep;
;             if constexpr (SP2) {
;             PG8_LDB(B0, 0, 0); PG8_LDB(B1, 0, 1); PG8_SCHED; PG8_LDA(At, 0, 0); PG8_STAGE(PG8_SA(1, 1), a1 + hstepA, voffA);
;             PG8_WAIT_V(8); PG8_WAIT_L(0); PG8_BAR; PG8_MMA(0, 0, At, B0); PG8_MMA(0, 1, At, B1); PG8_BAR; PG8_SCHED;
;             PG8_LDA(At, 0, 1); PG8_STAGE(PG8_SB(0, 0), b2, voffB); PG8_STAGE(PG8_SB(0, 1), b2 + hstepB, voffB); PG8_STAGE(PG8_SA(0, 0), a2, voffA);
.LBB0_1783:
	v_add_u32_e32 v0, s64, v208
	ds_read_b128 v[130:133], v0
	ds_read_b128 v[134:137], v0 offset:1024
	ds_read_b128 v[138:141], v0 offset:2048
	ds_read_b128 v[142:145], v0 offset:3072
	v_add_u32_e32 v0, s70, v208
	ds_read_b128 v[146:149], v0
	ds_read_b128 v[150:153], v0 offset:1024
	ds_read_b128 v[154:157], v0 offset:2048
	ds_read_b128 v[158:161], v0 offset:3072
	s_add_u32 s14, s12, 0xfff80080
	s_addc_u32 s15, s13, -1
	s_cmp_eq_u32 vcc_lo, 28
	s_cselect_b32 s47, s2, s15
	s_cselect_b32 s46, s3, s14
	s_cselect_b32 s15, s9, s41
	s_cselect_b32 s14, s11, s37
	s_cselect_b32 s100, -1, 0
	s_andn2_b32 s100, s100, s101
	s_add_i32 m0, s73, 0xc000
	ds_read_b128 v[162:165], v209
	ds_read_b128 v[166:169], v209 offset:1024
	ds_read_b128 v[170:173], v209 offset:2048
	ds_read_b128 v[174:177], v209 offset:3072
	ds_read_b128 v[190:193], v209 offset:4096
	ds_read_b128 v[194:197], v209 offset:5120
	ds_read_b128 v[198:201], v209 offset:6144
	ds_read_b128 v[202:205], v209 offset:7168
	global_load_lds_dwordx4 v186, s[12:13]
	s_add_i32 m0, s73, 0xe000
	s_nop 0
	global_load_lds_dwordx4 v188, s[12:13]
	s_waitcnt vmcnt(8)
	s_waitcnt lgkmcnt(0)
	s_setprio 1
	s_barrier
	v_mfma_f32_16x16x32_bf16 v[126:129], v[130:133], v[162:165], v[126:129]
	v_mfma_f32_16x16x32_bf16 v[94:97], v[138:141], v[162:165], v[94:97]
	v_mfma_f32_16x16x32_bf16 v[110:113], v[130:133], v[170:173], v[110:113]
	v_mfma_f32_16x16x32_bf16 v[70:73], v[138:141], v[170:173], v[70:73]
	v_mfma_f32_16x16x32_bf16 v[106:109], v[130:133], v[190:193], v[106:109]
	v_mfma_f32_16x16x32_bf16 v[66:69], v[138:141], v[190:193], v[66:69]
	v_mfma_f32_16x16x32_bf16 v[118:121], v[130:133], v[198:201], v[118:121]
	v_mfma_f32_16x16x32_bf16 v[86:89], v[138:141], v[198:201], v[86:89]
	v_mfma_f32_16x16x32_bf16 v[126:129], v[134:137], v[166:169], v[126:129]
	v_mfma_f32_16x16x32_bf16 v[94:97], v[142:145], v[166:169], v[94:97]
	v_mfma_f32_16x16x32_bf16 v[110:113], v[134:137], v[174:177], v[110:113]
	v_mfma_f32_16x16x32_bf16 v[70:73], v[142:145], v[174:177], v[70:73]
	v_mfma_f32_16x16x32_bf16 v[106:109], v[134:137], v[194:197], v[106:109]
	v_mfma_f32_16x16x32_bf16 v[66:69], v[142:145], v[194:197], v[66:69]
	v_mfma_f32_16x16x32_bf16 v[118:121], v[134:137], v[202:205], v[118:121]
	v_mfma_f32_16x16x32_bf16 v[86:89], v[142:145], v[202:205], v[86:89]
	v_mfma_f32_16x16x32_bf16 v[122:125], v[146:149], v[162:165], v[122:125]
	v_mfma_f32_16x16x32_bf16 v[90:93], v[154:157], v[162:165], v[90:93]
	v_mfma_f32_16x16x32_bf16 v[102:105], v[146:149], v[170:173], v[102:105]
	v_mfma_f32_16x16x32_bf16 v[62:65], v[154:157], v[170:173], v[62:65]
	v_mfma_f32_16x16x32_bf16 v[98:101], v[146:149], v[190:193], v[98:101]
	v_mfma_f32_16x16x32_bf16 v[58:61], v[154:157], v[190:193], v[58:61]
	v_mfma_f32_16x16x32_bf16 v[114:117], v[146:149], v[198:201], v[114:117]
	v_mfma_f32_16x16x32_bf16 v[82:85], v[154:157], v[198:201], v[82:85]
	v_mfma_f32_16x16x32_bf16 v[122:125], v[150:153], v[166:169], v[122:125]
	v_mfma_f32_16x16x32_bf16 v[90:93], v[158:161], v[166:169], v[90:93]
	v_mfma_f32_16x16x32_bf16 v[102:105], v[150:153], v[174:177], v[102:105]
	v_mfma_f32_16x16x32_bf16 v[62:65], v[158:161], v[174:177], v[62:65]
	v_mfma_f32_16x16x32_bf16 v[98:101], v[150:153], v[194:197], v[98:101]
	v_mfma_f32_16x16x32_bf16 v[58:61], v[158:161], v[194:197], v[58:61]
	v_mfma_f32_16x16x32_bf16 v[114:117], v[150:153], v[202:205], v[114:117]
	v_mfma_f32_16x16x32_bf16 v[82:85], v[158:161], v[202:205], v[82:85]
	s_barrier
	s_setprio 0
	s_mov_b32 m0, s68
	s_add_u32 s22, s14, 0x80000
	s_addc_u32 s23, s15, 0
	ds_read_b128 v[162:165], v209 offset:16384
	ds_read_b128 v[166:169], v209 offset:17408
	ds_read_b128 v[170:173], v209 offset:18432
	ds_read_b128 v[174:177], v209 offset:19456
	ds_read_b128 v[190:193], v209 offset:20480
	ds_read_b128 v[194:197], v209 offset:21504
	ds_read_b128 v[198:201], v209 offset:22528
	ds_read_b128 v[202:205], v209 offset:23552
	s_cmp_lg_u32 s100, 0
	s_cbranch_scc1 .Ltl_up_0s
	global_load_lds_dwordx4 v180, s[14:15]
	s_mov_b32 m0, s69
	s_nop 0
	global_load_lds_dwordx4 v184, s[14:15]
	s_mov_b32 m0, s71
	s_nop 0
	global_load_lds_dwordx4 v180, s[22:23]
	s_mov_b32 m0, s72
	s_nop 0
	global_load_lds_dwordx4 v184, s[22:23]
	s_mov_b32 m0, s73
	s_nop 0
	global_load_lds_dwordx4 v178, s[46:47]
	s_mov_b32 m0, s74
	s_nop 0
	global_load_lds_dwordx4 v182, s[46:47]
	s_waitcnt vmcnt(8)
	s_branch .Ltl_up_0d

; #define PG8_STAGE(bufoff, gbase, voff) do { _Pragma("unroll") for (int _i = 0; _i < 2; ++_i) \
;         __builtin_amdgcn_global_load_lds((const unsigned*)((const char*)(gbase) + (voff)[_i]), (LAS unsigned*)(lds + (bufoff) + ldsw + _i * 8192), 16, 0, 0); } while (0)
; #define PG8_LDA(dst, b, h) do { _Pragma("unroll") for (int m = 0; m < NM; ++m) _Pragma("unroll") for (int k = 0; k < 2; ++k) dst[m][k] = *(const LAS bf16x8*)(lds + PG8_SA(b, h) + aoff + m * 2048 + k * 1024); } while (0)
; #define PG8_LDB(dst, b, h) do { _Pragma("unroll") for (int n = 0; n < 2; ++n) _Pragma("unroll") for (int k = 0; k < 2; ++k) dst[n][k] = *(const LAS bf16x8*)(lds + PG8_SB(b, h) + boff + n * 2048 + k * 1024); } while (0)
; #define PG8_MMA(ai, bj, At, Bt) do { __builtin_amdgcn_s_setprio(1); _Pragma("unroll") for (int m = 0; m < NM; ++m) _Pragma("unroll") for (int n = 0; n < 2; ++n) _Pragma("unroll") for (int k = 0; k < 2; ++k) \
;         acc[ai][bj][m][n] = __builtin_amdgcn_mfma_f32_16x16x32_bf16(Bt[n][k], At[m][k], acc[ai][bj][m][n], 0, 0, 0); __builtin_amdgcn_s_setprio(0); } while (0)
; #define PG8_WAIT_V(n) asm volatile("s_waitcnt vmcnt(" #n ")" ::: "memory")
; #define PG8_WAIT_L(n) asm volatile("s_waitcnt lgkmcnt(" #n ")" ::: "memory")
; #define PG8_BAR __builtin_amdgcn_s_barrier()
; #define PG8_SCHED __builtin_amdgcn_sched_barrier(0)
;     ...
;             PG8_WAIT_V(8); PG8_WAIT_L(0); PG8_BAR; PG8_MMA(1, 0, At, B0); PG8_MMA(1, 1, At, B1); PG8_BAR; PG8_SCHED;
;             PG8_LDB(B0, 1, 0); PG8_LDB(B1, 1, 1); PG8_SCHED; PG8_LDA(At, 1, 0); PG8_STAGE(PG8_SA(0, 1), a2 + hstepA, voffA);
.Ltl_up_0d:
	s_waitcnt lgkmcnt(0)
	s_setprio 1
	s_barrier
	v_mfma_f32_16x16x32_bf16 v[46:49], v[130:133], v[162:165], v[46:49]
	v_mfma_f32_16x16x32_bf16 v[22:25], v[138:141], v[162:165], v[22:25]
	v_mfma_f32_16x16x32_bf16 v[42:45], v[130:133], v[170:173], v[42:45]
	v_mfma_f32_16x16x32_bf16 v[18:21], v[138:141], v[170:173], v[18:21]
	v_mfma_f32_16x16x32_bf16 v[38:41], v[130:133], v[190:193], v[38:41]
	v_mfma_f32_16x16x32_bf16 v[14:17], v[138:141], v[190:193], v[14:17]
	v_mfma_f32_16x16x32_bf16 v[78:81], v[130:133], v[198:201], v[78:81]
	v_mfma_f32_16x16x32_bf16 v[54:57], v[138:141], v[198:201], v[54:57]
	v_mfma_f32_16x16x32_bf16 v[46:49], v[134:137], v[166:169], v[46:49]
	v_mfma_f32_16x16x32_bf16 v[22:25], v[142:145], v[166:169], v[22:25]
	v_mfma_f32_16x16x32_bf16 v[42:45], v[134:137], v[174:177], v[42:45]
	v_mfma_f32_16x16x32_bf16 v[18:21], v[142:145], v[174:177], v[18:21]
	v_mfma_f32_16x16x32_bf16 v[38:41], v[134:137], v[194:197], v[38:41]
	v_mfma_f32_16x16x32_bf16 v[14:17], v[142:145], v[194:197], v[14:17]
	v_mfma_f32_16x16x32_bf16 v[78:81], v[134:137], v[202:205], v[78:81]
	v_mfma_f32_16x16x32_bf16 v[54:57], v[142:145], v[202:205], v[54:57]
	v_mfma_f32_16x16x32_bf16 v[34:37], v[146:149], v[162:165], v[34:37]
	v_mfma_f32_16x16x32_bf16 v[10:13], v[154:157], v[162:165], v[10:13]
	v_mfma_f32_16x16x32_bf16 v[30:33], v[146:149], v[170:173], v[30:33]
	v_mfma_f32_16x16x32_bf16 v[6:9], v[154:157], v[170:173], v[6:9]
	v_mfma_f32_16x16x32_bf16 v[26:29], v[146:149], v[190:193], v[26:29]
	v_mfma_f32_16x16x32_bf16 v[2:5], v[154:157], v[190:193], v[2:5]
	v_mfma_f32_16x16x32_bf16 v[74:77], v[146:149], v[198:201], v[74:77]
	v_mfma_f32_16x16x32_bf16 v[50:53], v[154:157], v[198:201], v[50:53]
	v_mfma_f32_16x16x32_bf16 v[34:37], v[150:153], v[166:169], v[34:37]
	v_mfma_f32_16x16x32_bf16 v[10:13], v[158:161], v[166:169], v[10:13]
	v_mfma_f32_16x16x32_bf16 v[30:33], v[150:153], v[174:177], v[30:33]
	v_mfma_f32_16x16x32_bf16 v[6:9], v[158:161], v[174:177], v[6:9]
	v_mfma_f32_16x16x32_bf16 v[26:29], v[150:153], v[194:197], v[26:29]
	v_mfma_f32_16x16x32_bf16 v[2:5], v[158:161], v[194:197], v[2:5]
	v_mfma_f32_16x16x32_bf16 v[74:77], v[150:153], v[202:205], v[74:77]
	v_mfma_f32_16x16x32_bf16 v[50:53], v[158:161], v[202:205], v[50:53]
	s_barrier
	s_setprio 0
	v_add_u32_e32 v0, s94, v208
	ds_read_b128 v[130:133], v0
	ds_read_b128 v[134:137], v0 offset:1024
	ds_read_b128 v[138:141], v0 offset:2048
	ds_read_b128 v[142:145], v0 offset:3072
	v_add_u32_e32 v0, s62, v208
	ds_read_b128 v[146:149], v0
	ds_read_b128 v[150:153], v0 offset:1024
	ds_read_b128 v[154:157], v0 offset:2048
	ds_read_b128 v[158:161], v0 offset:3072
	s_add_u32 s22, s46, 0x80000
	s_addc_u32 s23, s47, 0
	s_mov_b32 m0, s75
	ds_read_b128 v[162:165], v209 offset:32768
	ds_read_b128 v[166:169], v209 offset:33792
	ds_read_b128 v[170:173], v209 offset:34816
	ds_read_b128 v[174:177], v209 offset:35840
	ds_read_b128 v[190:193], v209 offset:36864
	ds_read_b128 v[194:197], v209 offset:37888
	ds_read_b128 v[198:201], v209 offset:38912
	ds_read_b128 v[202:205], v209 offset:39936
	s_cmp_lg_u32 s100, 0
	s_cbranch_scc1 .Ltl_up_1s
	global_load_lds_dwordx4 v178, s[22:23]
	s_mov_b32 m0, s80
	s_nop 0
	global_load_lds_dwordx4 v182, s[22:23]
	s_waitcnt vmcnt(8)
	s_branch .Ltl_up_1d

; #define PG8_STAGE(bufoff, gbase, voff) do { _Pragma("unroll") for (int _i = 0; _i < 2; ++_i) \
;         __builtin_amdgcn_global_load_lds((const unsigned*)((const char*)(gbase) + (voff)[_i]), (LAS unsigned*)(lds + (bufoff) + ldsw + _i * 8192), 16, 0, 0); } while (0)
; #define PG8_LDA(dst, b, h) do { _Pragma("unroll") for (int m = 0; m < NM; ++m) _Pragma("unroll") for (int k = 0; k < 2; ++k) dst[m][k] = *(const LAS bf16x8*)(lds + PG8_SA(b, h) + aoff + m * 2048 + k * 1024); } while (0)
; #define PG8_MMA(ai, bj, At, Bt) do { __builtin_amdgcn_s_setprio(1); _Pragma("unroll") for (int m = 0; m < NM; ++m) _Pragma("unroll") for (int n = 0; n < 2; ++n) _Pragma("unroll") for (int k = 0; k < 2; ++k) \
;         acc[ai][bj][m][n] = __builtin_amdgcn_mfma_f32_16x16x32_bf16(Bt[n][k], At[m][k], acc[ai][bj][m][n], 0, 0, 0); __builtin_amdgcn_s_setprio(0); } while (0)
; #define PG8_WAIT_V(n) asm volatile("s_waitcnt vmcnt(" #n ")" ::: "memory")
; #define PG8_WAIT_L(n) asm volatile("s_waitcnt lgkmcnt(" #n ")" ::: "memory")
; #define PG8_BAR __builtin_amdgcn_s_barrier()
; #define PG8_SCHED __builtin_amdgcn_sched_barrier(0)
;     ...
;             PG8_WAIT_V(8); PG8_WAIT_L(0); PG8_BAR; PG8_MMA(0, 0, At, B0); PG8_MMA(0, 1, At, B1); PG8_BAR; PG8_SCHED;
;             PG8_LDA(At, 1, 1); PG8_STAGE(PG8_SB(1, 0), b3, voffB); PG8_STAGE(PG8_SB(1, 1), b3 + hstepB, voffB); PG8_STAGE(PG8_SA(1, 0), a3, voffA);
.Ltl_up_1d:
	s_waitcnt lgkmcnt(0)
	s_setprio 1
	s_barrier
	v_mfma_f32_16x16x32_bf16 v[126:129], v[130:133], v[162:165], v[126:129]
	v_mfma_f32_16x16x32_bf16 v[94:97], v[138:141], v[162:165], v[94:97]
	v_mfma_f32_16x16x32_bf16 v[110:113], v[130:133], v[170:173], v[110:113]
	v_mfma_f32_16x16x32_bf16 v[70:73], v[138:141], v[170:173], v[70:73]
	v_mfma_f32_16x16x32_bf16 v[106:109], v[130:133], v[190:193], v[106:109]
	v_mfma_f32_16x16x32_bf16 v[66:69], v[138:141], v[190:193], v[66:69]
	v_mfma_f32_16x16x32_bf16 v[118:121], v[130:133], v[198:201], v[118:121]
	v_mfma_f32_16x16x32_bf16 v[86:89], v[138:141], v[198:201], v[86:89]
	v_mfma_f32_16x16x32_bf16 v[126:129], v[134:137], v[166:169], v[126:129]
	v_mfma_f32_16x16x32_bf16 v[94:97], v[142:145], v[166:169], v[94:97]
	v_mfma_f32_16x16x32_bf16 v[110:113], v[134:137], v[174:177], v[110:113]
	v_mfma_f32_16x16x32_bf16 v[70:73], v[142:145], v[174:177], v[70:73]
	v_mfma_f32_16x16x32_bf16 v[106:109], v[134:137], v[194:197], v[106:109]
	v_mfma_f32_16x16x32_bf16 v[66:69], v[142:145], v[194:197], v[66:69]
	v_mfma_f32_16x16x32_bf16 v[118:121], v[134:137], v[202:205], v[118:121]
	v_mfma_f32_16x16x32_bf16 v[86:89], v[142:145], v[202:205], v[86:89]
	v_mfma_f32_16x16x32_bf16 v[122:125], v[146:149], v[162:165], v[122:125]
	v_mfma_f32_16x16x32_bf16 v[90:93], v[154:157], v[162:165], v[90:93]
	v_mfma_f32_16x16x32_bf16 v[102:105], v[146:149], v[170:173], v[102:105]
	v_mfma_f32_16x16x32_bf16 v[62:65], v[154:157], v[170:173], v[62:65]
	v_mfma_f32_16x16x32_bf16 v[98:101], v[146:149], v[190:193], v[98:101]
	v_mfma_f32_16x16x32_bf16 v[58:61], v[154:157], v[190:193], v[58:61]
	v_mfma_f32_16x16x32_bf16 v[114:117], v[146:149], v[198:201], v[114:117]
	v_mfma_f32_16x16x32_bf16 v[82:85], v[154:157], v[198:201], v[82:85]
	v_mfma_f32_16x16x32_bf16 v[122:125], v[150:153], v[166:169], v[122:125]
	v_mfma_f32_16x16x32_bf16 v[90:93], v[158:161], v[166:169], v[90:93]
	v_mfma_f32_16x16x32_bf16 v[102:105], v[150:153], v[174:177], v[102:105]
	v_mfma_f32_16x16x32_bf16 v[62:65], v[158:161], v[174:177], v[62:65]
	v_mfma_f32_16x16x32_bf16 v[98:101], v[150:153], v[194:197], v[98:101]
	v_mfma_f32_16x16x32_bf16 v[58:61], v[158:161], v[194:197], v[58:61]
	v_mfma_f32_16x16x32_bf16 v[114:117], v[150:153], v[202:205], v[114:117]
	v_mfma_f32_16x16x32_bf16 v[82:85], v[158:161], v[202:205], v[82:85]
	s_barrier
	s_setprio 0
	s_mov_b32 m0, s51
	s_add_u32 s22, s14, s66
	s_addc_u32 s23, s15, s67
	s_add_u32 s14, s14, 0x80080
	s_addc_u32 s15, s15, 0
	ds_read_b128 v[162:165], v209 offset:49152
	ds_read_b128 v[166:169], v209 offset:50176
	ds_read_b128 v[170:173], v209 offset:51200
	ds_read_b128 v[174:177], v209 offset:52224
	ds_read_b128 v[190:193], v209 offset:53248
	ds_read_b128 v[194:197], v209 offset:54272
	ds_read_b128 v[198:201], v209 offset:55296
	ds_read_b128 v[202:205], v209 offset:56320
	s_cmp_lg_u32 s100, 0
	s_cbranch_scc1 .Ltl_up_2s
	global_load_lds_dwordx4 v180, s[22:23]
	s_mov_b32 m0, s95
	s_nop 0
	global_load_lds_dwordx4 v184, s[22:23]
	s_add_u32 s22, s46, s66
	s_addc_u32 s23, s47, s67
	s_mov_b32 m0, s50
	s_nop 0
	global_load_lds_dwordx4 v180, s[14:15]
	s_mov_b32 m0, s49
	s_nop 0
	global_load_lds_dwordx4 v184, s[14:15]
	s_mov_b32 m0, s58
	s_nop 0
	global_load_lds_dwordx4 v178, s[22:23]
	s_mov_b32 m0, s59
	s_nop 0
	global_load_lds_dwordx4 v182, s[22:23]
	s_waitcnt vmcnt(8)
	s_branch .Ltl_up_2d

; #define PG8_MMA(ai, bj, At, Bt) do { __builtin_amdgcn_s_setprio(1); _Pragma("unroll") for (int m = 0; m < NM; ++m) _Pragma("unroll") for (int n = 0; n < 2; ++n) _Pragma("unroll") for (int k = 0; k < 2; ++k) \
;         acc[ai][bj][m][n] = __builtin_amdgcn_mfma_f32_16x16x32_bf16(Bt[n][k], At[m][k], acc[ai][bj][m][n], 0, 0, 0); __builtin_amdgcn_s_setprio(0); } while (0)
; #define PG8_WAIT_V(n) asm volatile("s_waitcnt vmcnt(" #n ")" ::: "memory")
; #define PG8_WAIT_L(n) asm volatile("s_waitcnt lgkmcnt(" #n ")" ::: "memory")
; #define PG8_BAR __builtin_amdgcn_s_barrier()
; #define PG8_SCHED __builtin_amdgcn_sched_barrier(0)
;     ...
;             PG8_WAIT_V(8); PG8_WAIT_L(0); PG8_BAR; PG8_MMA(1, 0, At, B0); PG8_MMA(1, 1, At, B1); PG8_BAR; PG8_SCHED;
;     ...
;         }
;         if constexpr (ALIGN_EPI) { if (wr == 0) PG8_BAR; }
.Ltl_up_2d:
	s_waitcnt lgkmcnt(0)
	s_setprio 1
	s_barrier
	v_mfma_f32_16x16x32_bf16 v[46:49], v[130:133], v[162:165], v[46:49]
	v_mfma_f32_16x16x32_bf16 v[22:25], v[138:141], v[162:165], v[22:25]
	v_mfma_f32_16x16x32_bf16 v[42:45], v[130:133], v[170:173], v[42:45]
	v_mfma_f32_16x16x32_bf16 v[18:21], v[138:141], v[170:173], v[18:21]
	v_mfma_f32_16x16x32_bf16 v[38:41], v[130:133], v[190:193], v[38:41]
	v_mfma_f32_16x16x32_bf16 v[14:17], v[138:141], v[190:193], v[14:17]
	v_mfma_f32_16x16x32_bf16 v[78:81], v[130:133], v[198:201], v[78:81]
	v_mfma_f32_16x16x32_bf16 v[54:57], v[138:141], v[198:201], v[54:57]
	v_mfma_f32_16x16x32_bf16 v[46:49], v[134:137], v[166:169], v[46:49]
	v_mfma_f32_16x16x32_bf16 v[22:25], v[142:145], v[166:169], v[22:25]
	v_mfma_f32_16x16x32_bf16 v[42:45], v[134:137], v[174:177], v[42:45]
	v_mfma_f32_16x16x32_bf16 v[18:21], v[142:145], v[174:177], v[18:21]
	v_mfma_f32_16x16x32_bf16 v[38:41], v[134:137], v[194:197], v[38:41]
	v_mfma_f32_16x16x32_bf16 v[14:17], v[142:145], v[194:197], v[14:17]
	v_mfma_f32_16x16x32_bf16 v[78:81], v[134:137], v[202:205], v[78:81]
	v_mfma_f32_16x16x32_bf16 v[54:57], v[142:145], v[202:205], v[54:57]
	v_mfma_f32_16x16x32_bf16 v[34:37], v[146:149], v[162:165], v[34:37]
	v_mfma_f32_16x16x32_bf16 v[10:13], v[154:157], v[162:165], v[10:13]
	v_mfma_f32_16x16x32_bf16 v[30:33], v[146:149], v[170:173], v[30:33]
	v_mfma_f32_16x16x32_bf16 v[6:9], v[154:157], v[170:173], v[6:9]
	v_mfma_f32_16x16x32_bf16 v[26:29], v[146:149], v[190:193], v[26:29]
	v_mfma_f32_16x16x32_bf16 v[2:5], v[154:157], v[190:193], v[2:5]
	v_mfma_f32_16x16x32_bf16 v[74:77], v[146:149], v[198:201], v[74:77]
	v_mfma_f32_16x16x32_bf16 v[50:53], v[154:157], v[198:201], v[50:53]
	v_mfma_f32_16x16x32_bf16 v[34:37], v[150:153], v[166:169], v[34:37]
	v_mfma_f32_16x16x32_bf16 v[10:13], v[158:161], v[166:169], v[10:13]
	v_mfma_f32_16x16x32_bf16 v[30:33], v[150:153], v[174:177], v[30:33]
	v_mfma_f32_16x16x32_bf16 v[6:9], v[158:161], v[174:177], v[6:9]
	v_mfma_f32_16x16x32_bf16 v[26:29], v[150:153], v[194:197], v[26:29]
	v_mfma_f32_16x16x32_bf16 v[2:5], v[158:161], v[194:197], v[2:5]
	v_mfma_f32_16x16x32_bf16 v[74:77], v[150:153], v[202:205], v[74:77]
	v_mfma_f32_16x16x32_bf16 v[50:53], v[158:161], v[202:205], v[50:53]
	s_barrier
	s_setprio 0
	s_add_i32 vcc_lo, vcc_lo, 2
	s_add_u32 s12, s12, 0x100
	s_addc_u32 s13, s13, 0
	s_add_u32 s37, s37, 0x100
	s_addc_u32 s41, s41, 0
	s_cmp_gt_u32 vcc_lo, 29
	s_cbranch_scc0 .LBB0_1783
	s_and_b64 vcc, exec, s[24:25]
	s_cbranch_vccz .LBB0_1786
	s_barrier

; #define PG8_STAGE(bufoff, gbase, voff) do { _Pragma("unroll") for (int _i = 0; _i < 2; ++_i) \
;         __builtin_amdgcn_global_load_lds((const unsigned*)((const char*)(gbase) + (voff)[_i]), (LAS unsigned*)(lds + (bufoff) + ldsw + _i * 8192), 16, 0, 0); } while (0)
; #define PG8_LDA(dst, b, h) do { _Pragma("unroll") for (int m = 0; m < NM; ++m) _Pragma("unroll") for (int k = 0; k < 2; ++k) dst[m][k] = *(const LAS bf16x8*)(lds + PG8_SA(b, h) + aoff + m * 2048 + k * 1024); } while (0)
; #define PG8_MMA(ai, bj, At, Bt) do { __builtin_amdgcn_s_setprio(1); _Pragma("unroll") for (int m = 0; m < NM; ++m) _Pragma("unroll") for (int n = 0; n < 2; ++n) _Pragma("unroll") for (int k = 0; k < 2; ++k) \
;         acc[ai][bj][m][n] = __builtin_amdgcn_mfma_f32_16x16x32_bf16(Bt[n][k], At[m][k], acc[ai][bj][m][n], 0, 0, 0); __builtin_amdgcn_s_setprio(0); } while (0)
; #define PG8_WAIT_V(n) asm volatile("s_waitcnt vmcnt(" #n ")" ::: "memory")
; #define PG8_WAIT_L(n) asm volatile("s_waitcnt lgkmcnt(" #n ")" ::: "memory")
; #define PG8_BAR __builtin_amdgcn_s_barrier()
; #define PG8_SCHED __builtin_amdgcn_sched_barrier(0)
;     ...
;             PG8_WAIT_V(8); PG8_WAIT_L(0); PG8_BAR; PG8_MMA(0, 0, At, B0); PG8_MMA(0, 1, At, B1); PG8_BAR; PG8_SCHED;
;             PG8_LDA(At, 0, 1); PG8_STAGE(PG8_SB(0, 0), b2, voffB); PG8_STAGE(PG8_SB(0, 1), b2 + hstepB, voffB); PG8_STAGE(PG8_SA(0, 0), a2, voffA);
.Lnm3d_done0:
	s_waitcnt lgkmcnt(0)
	s_setprio 1
	s_barrier
	v_mfma_f32_16x16x32_bf16 v[110:113], v[90:93], v[130:133], v[110:113]
	v_mfma_f32_16x16x32_bf16 v[106:109], v[98:101], v[130:133], v[106:109]
	v_mfma_f32_16x16x32_bf16 v[78:81], v[90:93], v[138:141], v[78:81]
	v_mfma_f32_16x16x32_bf16 v[74:77], v[98:101], v[138:141], v[74:77]
	v_mfma_f32_16x16x32_bf16 v[62:65], v[90:93], v[156:159], v[62:65]
	v_mfma_f32_16x16x32_bf16 v[58:61], v[98:101], v[156:159], v[58:61]
	v_mfma_f32_16x16x32_bf16 v[110:113], v[94:97], v[134:137], v[110:113]
	v_mfma_f32_16x16x32_bf16 v[106:109], v[102:105], v[134:137], v[106:109]
	v_mfma_f32_16x16x32_bf16 v[78:81], v[94:97], v[152:155], v[78:81]
	v_mfma_f32_16x16x32_bf16 v[74:77], v[102:105], v[152:155], v[74:77]
	v_mfma_f32_16x16x32_bf16 v[62:65], v[94:97], v[160:163], v[62:65]
	v_mfma_f32_16x16x32_bf16 v[58:61], v[102:105], v[160:163], v[58:61]
	v_mfma_f32_16x16x32_bf16 v[86:89], v[114:117], v[130:133], v[86:89]
	v_mfma_f32_16x16x32_bf16 v[82:85], v[122:125], v[130:133], v[82:85]
	v_mfma_f32_16x16x32_bf16 v[70:73], v[114:117], v[138:141], v[70:73]
	v_mfma_f32_16x16x32_bf16 v[66:69], v[122:125], v[138:141], v[66:69]
	v_mfma_f32_16x16x32_bf16 v[54:57], v[114:117], v[156:159], v[54:57]
	v_mfma_f32_16x16x32_bf16 v[50:53], v[122:125], v[156:159], v[50:53]
	v_mfma_f32_16x16x32_bf16 v[86:89], v[118:121], v[134:137], v[86:89]
	v_mfma_f32_16x16x32_bf16 v[82:85], v[126:129], v[134:137], v[82:85]
	v_mfma_f32_16x16x32_bf16 v[70:73], v[118:121], v[152:155], v[70:73]
	v_mfma_f32_16x16x32_bf16 v[66:69], v[126:129], v[152:155], v[66:69]
	v_mfma_f32_16x16x32_bf16 v[54:57], v[118:121], v[160:163], v[54:57]
	v_mfma_f32_16x16x32_bf16 v[50:53], v[126:129], v[160:163], v[50:53]
	s_barrier
	s_setprio 0
	s_mov_b32 m0, s27
	v_lshl_add_u64 v[164:165], s[18:19], 0, v[0:1]
	s_add_u32 s14, s18, 0x160000
	s_addc_u32 s15, s19, 0
	ds_read_b128 v[130:133], v167 offset:16384
	ds_read_b128 v[134:137], v167 offset:17408
	ds_read_b128 v[138:141], v167 offset:18432
	ds_read_b128 v[152:155], v167 offset:19456
	ds_read_b128 v[156:159], v167 offset:20480
	ds_read_b128 v[160:163], v167 offset:21504
	s_cmp_lg_u32 s100, 0
	s_cbranch_scc1 .Ltl_dn_0s
	global_load_lds_dwordx4 v0, s[18:19]
	v_lshl_add_u64 v[168:169], s[18:19], 0, v[146:147]
	s_mov_b32 m0, s28
	s_nop 0
	global_load_lds_dwordx4 v146, s[18:19]
	s_mov_b32 m0, s30
	v_lshl_add_u64 v[172:173], s[20:21], 0, v[144:145]
	global_load_lds_dwordx4 v0, s[14:15]
	s_mov_b32 m0, s31
	s_nop 0
	global_load_lds_dwordx4 v146, s[14:15]
	v_lshl_add_u64 v[170:171], s[20:21], 0, v[142:143]
	s_mov_b32 m0, s34
	s_nop 0
	global_load_lds_dwordx4 v142, s[20:21]
	s_mov_b32 m0, s35
	s_nop 0
	s_and_b64 vcc, exec, s[8:9]
	s_cbranch_vccz .Lnm3d_skip1
	global_load_lds_dwordx4 v144, s[20:21]
	s_waitcnt vmcnt(8)
	s_branch .Lnm3d_done1

; #define PG8_STAGE(bufoff, gbase, voff) do { _Pragma("unroll") for (int _i = 0; _i < 2; ++_i) \
;         __builtin_amdgcn_global_load_lds((const unsigned*)((const char*)(gbase) + (voff)[_i]), (LAS unsigned*)(lds + (bufoff) + ldsw + _i * 8192), 16, 0, 0); } while (0)
; #define PG8_LDA(dst, b, h) do { _Pragma("unroll") for (int m = 0; m < NM; ++m) _Pragma("unroll") for (int k = 0; k < 2; ++k) dst[m][k] = *(const LAS bf16x8*)(lds + PG8_SA(b, h) + aoff + m * 2048 + k * 1024); } while (0)
; #define PG8_LDB(dst, b, h) do { _Pragma("unroll") for (int n = 0; n < 2; ++n) _Pragma("unroll") for (int k = 0; k < 2; ++k) dst[n][k] = *(const LAS bf16x8*)(lds + PG8_SB(b, h) + boff + n * 2048 + k * 1024); } while (0)
; #define PG8_MMA(ai, bj, At, Bt) do { __builtin_amdgcn_s_setprio(1); _Pragma("unroll") for (int m = 0; m < NM; ++m) _Pragma("unroll") for (int n = 0; n < 2; ++n) _Pragma("unroll") for (int k = 0; k < 2; ++k) \
;         acc[ai][bj][m][n] = __builtin_amdgcn_mfma_f32_16x16x32_bf16(Bt[n][k], At[m][k], acc[ai][bj][m][n], 0, 0, 0); __builtin_amdgcn_s_setprio(0); } while (0)
; #define PG8_WAIT_V(n) asm volatile("s_waitcnt vmcnt(" #n ")" ::: "memory")
; #define PG8_WAIT_L(n) asm volatile("s_waitcnt lgkmcnt(" #n ")" ::: "memory")
; #define PG8_BAR __builtin_amdgcn_s_barrier()
; #define PG8_SCHED __builtin_amdgcn_sched_barrier(0)
;     ...
;             PG8_WAIT_V(8); PG8_WAIT_L(0); PG8_BAR; PG8_MMA(1, 0, At, B0); PG8_MMA(1, 1, At, B1); PG8_BAR; PG8_SCHED;
;             PG8_LDB(B0, 1, 0); PG8_LDB(B1, 1, 1); PG8_SCHED; PG8_LDA(At, 1, 0); PG8_STAGE(PG8_SA(0, 1), a2 + hstepA, voffA);
.Ltl_dn_0d:
	s_waitcnt lgkmcnt(0)
	s_setprio 1
	s_barrier
	v_mfma_f32_16x16x32_bf16 v[46:49], v[90:93], v[130:133], v[46:49]
	v_mfma_f32_16x16x32_bf16 v[42:45], v[98:101], v[130:133], v[42:45]
	v_mfma_f32_16x16x32_bf16 v[30:33], v[90:93], v[138:141], v[30:33]
	v_mfma_f32_16x16x32_bf16 v[26:29], v[98:101], v[138:141], v[26:29]
	v_mfma_f32_16x16x32_bf16 v[14:17], v[90:93], v[156:159], v[14:17]
	v_mfma_f32_16x16x32_bf16 v[10:13], v[98:101], v[156:159], v[10:13]
	v_mfma_f32_16x16x32_bf16 v[46:49], v[94:97], v[134:137], v[46:49]
	v_mfma_f32_16x16x32_bf16 v[42:45], v[102:105], v[134:137], v[42:45]
	v_mfma_f32_16x16x32_bf16 v[30:33], v[94:97], v[152:155], v[30:33]
	v_mfma_f32_16x16x32_bf16 v[26:29], v[102:105], v[152:155], v[26:29]
	v_mfma_f32_16x16x32_bf16 v[14:17], v[94:97], v[160:163], v[14:17]
	v_mfma_f32_16x16x32_bf16 v[10:13], v[102:105], v[160:163], v[10:13]
	v_mfma_f32_16x16x32_bf16 v[38:41], v[114:117], v[130:133], v[38:41]
	v_mfma_f32_16x16x32_bf16 v[34:37], v[122:125], v[130:133], v[34:37]
	v_mfma_f32_16x16x32_bf16 v[22:25], v[114:117], v[138:141], v[22:25]
	v_mfma_f32_16x16x32_bf16 v[18:21], v[122:125], v[138:141], v[18:21]
	v_mfma_f32_16x16x32_bf16 v[6:9], v[114:117], v[156:159], v[6:9]
	v_mfma_f32_16x16x32_bf16 v[2:5], v[122:125], v[156:159], v[2:5]
	v_mfma_f32_16x16x32_bf16 v[38:41], v[118:121], v[134:137], v[38:41]
	v_mfma_f32_16x16x32_bf16 v[34:37], v[126:129], v[134:137], v[34:37]
	v_mfma_f32_16x16x32_bf16 v[22:25], v[118:121], v[152:155], v[22:25]
	v_mfma_f32_16x16x32_bf16 v[18:21], v[126:129], v[152:155], v[18:21]
	v_mfma_f32_16x16x32_bf16 v[6:9], v[118:121], v[160:163], v[6:9]
	v_mfma_f32_16x16x32_bf16 v[2:5], v[126:129], v[160:163], v[2:5]
	s_barrier
	s_setprio 0
	v_add_u32_e32 v102, s38, v166
	v_add_u32_e32 v126, s45, v166
	ds_read_b128 v[90:93], v102
	ds_read_b128 v[94:97], v102 offset:1024
	ds_read_b128 v[98:101], v102 offset:2048
	ds_read_b128 v[102:105], v102 offset:3072
	ds_read_b128 v[114:117], v126
	ds_read_b128 v[118:121], v126 offset:1024
	ds_read_b128 v[122:125], v126 offset:2048
	ds_read_b128 v[126:129], v126 offset:3072
	s_add_u32 s14, s20, 0x108000
	s_addc_u32 s15, s21, 0
	s_mov_b32 m0, s36
	ds_read_b128 v[130:133], v167 offset:32768
	ds_read_b128 v[134:137], v167 offset:33792
	ds_read_b128 v[138:141], v167 offset:34816
	ds_read_b128 v[152:155], v167 offset:35840
	ds_read_b128 v[156:159], v167 offset:36864
	ds_read_b128 v[160:163], v167 offset:37888
	s_cmp_lg_u32 s100, 0
	s_cbranch_scc1 .Ltl_dn_1s
	global_load_lds_dwordx4 v142, s[14:15]
	s_mov_b32 m0, s37
	s_nop 0
	s_and_b64 vcc, exec, s[8:9]
	s_cbranch_vccz .Lnm3d_skip2
	global_load_lds_dwordx4 v144, s[14:15]
	s_waitcnt vmcnt(8)
	s_branch .Lnm3d_done2

; #define PG8_STAGE(bufoff, gbase, voff) do { _Pragma("unroll") for (int _i = 0; _i < 2; ++_i) \
;         __builtin_amdgcn_global_load_lds((const unsigned*)((const char*)(gbase) + (voff)[_i]), (LAS unsigned*)(lds + (bufoff) + ldsw + _i * 8192), 16, 0, 0); } while (0)
; #define PG8_LDA(dst, b, h) do { _Pragma("unroll") for (int m = 0; m < NM; ++m) _Pragma("unroll") for (int k = 0; k < 2; ++k) dst[m][k] = *(const LAS bf16x8*)(lds + PG8_SA(b, h) + aoff + m * 2048 + k * 1024); } while (0)
; #define PG8_MMA(ai, bj, At, Bt) do { __builtin_amdgcn_s_setprio(1); _Pragma("unroll") for (int m = 0; m < NM; ++m) _Pragma("unroll") for (int n = 0; n < 2; ++n) _Pragma("unroll") for (int k = 0; k < 2; ++k) \
;         acc[ai][bj][m][n] = __builtin_amdgcn_mfma_f32_16x16x32_bf16(Bt[n][k], At[m][k], acc[ai][bj][m][n], 0, 0, 0); __builtin_amdgcn_s_setprio(0); } while (0)
; #define PG8_WAIT_V(n) asm volatile("s_waitcnt vmcnt(" #n ")" ::: "memory")
; #define PG8_WAIT_L(n) asm volatile("s_waitcnt lgkmcnt(" #n ")" ::: "memory")
; #define PG8_BAR __builtin_amdgcn_s_barrier()
; #define PG8_SCHED __builtin_amdgcn_sched_barrier(0)
;     ...
;             PG8_WAIT_V(8); PG8_WAIT_L(0); PG8_BAR; PG8_MMA(0, 0, At, B0); PG8_MMA(0, 1, At, B1); PG8_BAR; PG8_SCHED;
;             PG8_LDA(At, 1, 1); PG8_STAGE(PG8_SB(1, 0), b3, voffB); PG8_STAGE(PG8_SB(1, 1), b3 + hstepB, voffB); PG8_STAGE(PG8_SA(1, 0), a3, voffA);
.Ltl_dn_1d:
	s_waitcnt lgkmcnt(0)
	s_setprio 1
	s_barrier
	v_mfma_f32_16x16x32_bf16 v[110:113], v[90:93], v[130:133], v[110:113]
	v_mfma_f32_16x16x32_bf16 v[106:109], v[98:101], v[130:133], v[106:109]
	v_mfma_f32_16x16x32_bf16 v[78:81], v[90:93], v[138:141], v[78:81]
	v_mfma_f32_16x16x32_bf16 v[74:77], v[98:101], v[138:141], v[74:77]
	v_mfma_f32_16x16x32_bf16 v[62:65], v[90:93], v[156:159], v[62:65]
	v_mfma_f32_16x16x32_bf16 v[58:61], v[98:101], v[156:159], v[58:61]
	v_mfma_f32_16x16x32_bf16 v[110:113], v[94:97], v[134:137], v[110:113]
	v_mfma_f32_16x16x32_bf16 v[106:109], v[102:105], v[134:137], v[106:109]
	v_mfma_f32_16x16x32_bf16 v[78:81], v[94:97], v[152:155], v[78:81]
	v_mfma_f32_16x16x32_bf16 v[74:77], v[102:105], v[152:155], v[74:77]
	v_mfma_f32_16x16x32_bf16 v[62:65], v[94:97], v[160:163], v[62:65]
	v_mfma_f32_16x16x32_bf16 v[58:61], v[102:105], v[160:163], v[58:61]
	v_mfma_f32_16x16x32_bf16 v[86:89], v[114:117], v[130:133], v[86:89]
	v_mfma_f32_16x16x32_bf16 v[82:85], v[122:125], v[130:133], v[82:85]
	v_mfma_f32_16x16x32_bf16 v[70:73], v[114:117], v[138:141], v[70:73]
	v_mfma_f32_16x16x32_bf16 v[66:69], v[122:125], v[138:141], v[66:69]
	v_mfma_f32_16x16x32_bf16 v[54:57], v[114:117], v[156:159], v[54:57]
	v_mfma_f32_16x16x32_bf16 v[50:53], v[122:125], v[156:159], v[50:53]
	v_mfma_f32_16x16x32_bf16 v[86:89], v[118:121], v[134:137], v[86:89]
	v_mfma_f32_16x16x32_bf16 v[82:85], v[126:129], v[134:137], v[82:85]
	v_mfma_f32_16x16x32_bf16 v[70:73], v[118:121], v[152:155], v[70:73]
	v_mfma_f32_16x16x32_bf16 v[66:69], v[126:129], v[152:155], v[66:69]
	v_mfma_f32_16x16x32_bf16 v[54:57], v[118:121], v[160:163], v[54:57]
	v_mfma_f32_16x16x32_bf16 v[50:53], v[126:129], v[160:163], v[50:53]
	s_barrier
	s_setprio 0
	s_mov_b32 m0, s41
	v_lshl_add_u64 v[164:165], v[164:165], 0, s[66:67]
	s_add_u32 s14, s18, 0x160080
	s_addc_u32 s15, s19, 0
	ds_read_b128 v[130:133], v167 offset:49152
	ds_read_b128 v[134:137], v167 offset:50176
	ds_read_b128 v[138:141], v167 offset:51200
	ds_read_b128 v[152:155], v167 offset:52224
	ds_read_b128 v[156:159], v167 offset:53248
	ds_read_b128 v[160:163], v167 offset:54272
	s_cmp_lg_u32 s100, 0
	s_cbranch_scc1 .Ltl_dn_2s
	global_load_lds_dwordx4 v[164:165], off
	v_lshl_add_u64 v[164:165], v[168:169], 0, s[66:67]
	s_mov_b32 m0, s42
	s_nop 0
	global_load_lds_dwordx4 v[164:165], off
	s_mov_b32 m0, s46
	s_nop 0
	global_load_lds_dwordx4 v0, s[14:15]
	s_mov_b32 m0, s47
	s_nop 0
	global_load_lds_dwordx4 v146, s[14:15]
	v_lshl_add_u64 v[164:165], v[170:171], 0, s[66:67]
	s_mov_b32 m0, s43
	s_nop 0
	global_load_lds_dwordx4 v[164:165], off
	v_lshl_add_u64 v[164:165], v[172:173], 0, s[66:67]
	s_mov_b32 m0, s44
	s_nop 0
	s_and_b64 vcc, exec, s[8:9]
	s_cbranch_vccz .Lnm3d_skip3
	global_load_lds_dwordx4 v[164:165], off
	s_waitcnt vmcnt(8)
	s_branch .Lnm3d_done3

; #define PG8_MMA(ai, bj, At, Bt) do { __builtin_amdgcn_s_setprio(1); _Pragma("unroll") for (int m = 0; m < NM; ++m) _Pragma("unroll") for (int n = 0; n < 2; ++n) _Pragma("unroll") for (int k = 0; k < 2; ++k) \
;         acc[ai][bj][m][n] = __builtin_amdgcn_mfma_f32_16x16x32_bf16(Bt[n][k], At[m][k], acc[ai][bj][m][n], 0, 0, 0); __builtin_amdgcn_s_setprio(0); } while (0)
; #define PG8_WAIT_V(n) asm volatile("s_waitcnt vmcnt(" #n ")" ::: "memory")
; #define PG8_WAIT_L(n) asm volatile("s_waitcnt lgkmcnt(" #n ")" ::: "memory")
; #define PG8_BAR __builtin_amdgcn_s_barrier()
; #define PG8_SCHED __builtin_amdgcn_sched_barrier(0)
;     ...
;             PG8_WAIT_V(8); PG8_WAIT_L(0); PG8_BAR; PG8_MMA(1, 0, At, B0); PG8_MMA(1, 1, At, B1); PG8_BAR; PG8_SCHED;
;     ...
;         }
;         if constexpr (ALIGN_EPI) { if (wr == 0) PG8_BAR; }
.Ltl_dn_2d:
	s_waitcnt lgkmcnt(0)
	s_setprio 1
	s_barrier
	v_mfma_f32_16x16x32_bf16 v[46:49], v[90:93], v[130:133], v[46:49]
	v_mfma_f32_16x16x32_bf16 v[42:45], v[98:101], v[130:133], v[42:45]
	v_mfma_f32_16x16x32_bf16 v[30:33], v[90:93], v[138:141], v[30:33]
	v_mfma_f32_16x16x32_bf16 v[26:29], v[98:101], v[138:141], v[26:29]
	v_mfma_f32_16x16x32_bf16 v[14:17], v[90:93], v[156:159], v[14:17]
	v_mfma_f32_16x16x32_bf16 v[10:13], v[98:101], v[156:159], v[10:13]
	v_mfma_f32_16x16x32_bf16 v[46:49], v[94:97], v[134:137], v[46:49]
	v_mfma_f32_16x16x32_bf16 v[42:45], v[102:105], v[134:137], v[42:45]
	v_mfma_f32_16x16x32_bf16 v[30:33], v[94:97], v[152:155], v[30:33]
	v_mfma_f32_16x16x32_bf16 v[26:29], v[102:105], v[152:155], v[26:29]
	v_mfma_f32_16x16x32_bf16 v[14:17], v[94:97], v[160:163], v[14:17]
	v_mfma_f32_16x16x32_bf16 v[10:13], v[102:105], v[160:163], v[10:13]
	v_mfma_f32_16x16x32_bf16 v[38:41], v[114:117], v[130:133], v[38:41]
	v_mfma_f32_16x16x32_bf16 v[34:37], v[122:125], v[130:133], v[34:37]
	v_mfma_f32_16x16x32_bf16 v[22:25], v[114:117], v[138:141], v[22:25]
	v_mfma_f32_16x16x32_bf16 v[18:21], v[122:125], v[138:141], v[18:21]
	v_mfma_f32_16x16x32_bf16 v[6:9], v[114:117], v[156:159], v[6:9]
	v_mfma_f32_16x16x32_bf16 v[2:5], v[122:125], v[156:159], v[2:5]
	v_mfma_f32_16x16x32_bf16 v[38:41], v[118:121], v[134:137], v[38:41]
	v_mfma_f32_16x16x32_bf16 v[34:37], v[126:129], v[134:137], v[34:37]
	v_mfma_f32_16x16x32_bf16 v[22:25], v[118:121], v[152:155], v[22:25]
	v_mfma_f32_16x16x32_bf16 v[18:21], v[126:129], v[152:155], v[18:21]
	v_mfma_f32_16x16x32_bf16 v[6:9], v[118:121], v[160:163], v[6:9]
	v_mfma_f32_16x16x32_bf16 v[2:5], v[126:129], v[160:163], v[2:5]
	s_barrier
	s_setprio 0
	s_add_i32 s60, s60, 2
	s_add_u32 s2, s2, 0x100
	s_addc_u32 s3, s3, 0
	s_cmpk_gt_u32 s60, 0x55
	s_mov_b64 s[14:15], s[16:17]
	s_cbranch_scc0 .LBB0_2158
	s_and_b64 vcc, exec, s[8:9]
	s_cbranch_vccz .LBB0_2161
	s_barrier
